# P1/P12 swiglu epilogue: column-absmax and row-scale operands prefetched at unit start into K-loop-free VGPRs, epilogue copies them (no load wait after the last MFMA)
# speedup vs baseline: 1.0029x; 1.0029x over previous
.LBB0_219:
	v_mbcnt_lo_u32_b32 v240, -1, 0
	v_mbcnt_hi_u32_b32 v240, -1, v240
	s_lshl_b32 s4, s94, 7
	v_ashrrev_i32_e32 v242, 1, v240
	s_or_b32 s4, s4, s59
	v_and_b32_e32 v242, -8, v242
	v_add_u32_e32 v242, s4, v242
	v_ashrrev_i32_e32 v243, 31, v242
	v_lshlrev_b64 v[244:245], 2, v[242:243]
	v_lshl_add_u64 v[246:247], s[64:65], 0, v[244:245]
	v_lshl_add_u64 v[244:245], s[22:23], 0, v[244:245]
	s_lshl_b32 s4, s91, 8
	global_load_dwordx4 v[216:219], v[246:247], off
	global_load_dwordx4 v[220:223], v[246:247], off offset:16
	global_load_dwordx4 v[224:227], v[244:245], off
	global_load_dwordx4 v[228:231], v[244:245], off offset:16
	s_add_i32 s4, s4, s58
	v_and_or_b32 v242, v240, 15, s4
	v_ashrrev_i32_e32 v243, 31, v242
	v_lshl_add_u64 v[246:247], v[242:243], 2, s[10:11]
	global_load_dword v232, v[246:247], off
	global_load_dword v233, v[246:247], off offset:64
	global_load_dword v234, v[246:247], off offset:128
	global_load_dword v235, v[246:247], off offset:192
	global_load_dword v236, v[246:247], off offset:512
	global_load_dword v237, v[246:247], off offset:576
	global_load_dword v238, v[246:247], off offset:640
	global_load_dword v239, v[246:247], off offset:704
	v_mov_b32_e32 v123, 0
	s_lshl_b32 s89, s88, 20
	s_lshl_b32 s90, s83, 20
	s_andn2_b64 vcc, exec, s[12:13]
	v_mov_b32_e32 v122, v123
	v_mov_b32_e32 v121, v123
	v_mov_b32_e32 v120, v123
	v_mov_b32_e32 v115, v123
	v_mov_b32_e32 v114, v123
	v_mov_b32_e32 v113, v123
	v_mov_b32_e32 v112, v123
	v_mov_b32_e32 v107, v123
	v_mov_b32_e32 v106, v123
	v_mov_b32_e32 v105, v123
	v_mov_b32_e32 v104, v123
	v_mov_b32_e32 v99, v123
	v_mov_b32_e32 v98, v123
	v_mov_b32_e32 v97, v123
	v_mov_b32_e32 v96, v123
	v_mov_b32_e32 v91, v123
	v_mov_b32_e32 v90, v123
	v_mov_b32_e32 v89, v123
	v_mov_b32_e32 v88, v123
	v_mov_b32_e32 v83, v123
	v_mov_b32_e32 v82, v123
	v_mov_b32_e32 v81, v123
	v_mov_b32_e32 v80, v123
	v_mov_b32_e32 v75, v123
	v_mov_b32_e32 v74, v123
	v_mov_b32_e32 v73, v123
	v_mov_b32_e32 v72, v123
	v_mov_b32_e32 v67, v123
	v_mov_b32_e32 v66, v123
	v_mov_b32_e32 v65, v123
	v_mov_b32_e32 v64, v123
	v_mov_b32_e32 v127, v123
	v_mov_b32_e32 v126, v123
	v_mov_b32_e32 v125, v123
	v_mov_b32_e32 v124, v123
	v_mov_b32_e32 v119, v123
	v_mov_b32_e32 v118, v123
	v_mov_b32_e32 v117, v123
	v_mov_b32_e32 v116, v123
	v_mov_b32_e32 v111, v123
	v_mov_b32_e32 v110, v123
	v_mov_b32_e32 v109, v123
	v_mov_b32_e32 v108, v123
	v_mov_b32_e32 v103, v123
	v_mov_b32_e32 v102, v123
	v_mov_b32_e32 v101, v123
	v_mov_b32_e32 v100, v123
	v_mov_b32_e32 v95, v123
	v_mov_b32_e32 v94, v123
	v_mov_b32_e32 v93, v123
	v_mov_b32_e32 v92, v123
	v_mov_b32_e32 v87, v123
	v_mov_b32_e32 v86, v123
	v_mov_b32_e32 v85, v123
	v_mov_b32_e32 v84, v123
	v_mov_b32_e32 v79, v123
	v_mov_b32_e32 v78, v123
	v_mov_b32_e32 v77, v123
	v_mov_b32_e32 v76, v123
	v_mov_b32_e32 v71, v123
	v_mov_b32_e32 v70, v123
	v_mov_b32_e32 v69, v123
	v_mov_b32_e32 v68, v123
	v_mov_b32_e32 v59, v123
	v_mov_b32_e32 v58, v123
	v_mov_b32_e32 v57, v123
	v_mov_b32_e32 v56, v123
	v_mov_b32_e32 v51, v123
	v_mov_b32_e32 v50, v123
	v_mov_b32_e32 v49, v123
	v_mov_b32_e32 v48, v123
	v_mov_b32_e32 v43, v123
	v_mov_b32_e32 v42, v123
	v_mov_b32_e32 v41, v123
	v_mov_b32_e32 v40, v123
	v_mov_b32_e32 v35, v123
	v_mov_b32_e32 v34, v123
	v_mov_b32_e32 v33, v123
	v_mov_b32_e32 v32, v123
	v_mov_b32_e32 v27, v123
	v_mov_b32_e32 v26, v123
	v_mov_b32_e32 v25, v123
	v_mov_b32_e32 v24, v123
	v_mov_b32_e32 v19, v123
	v_mov_b32_e32 v18, v123
	v_mov_b32_e32 v17, v123
	v_mov_b32_e32 v16, v123
	v_mov_b32_e32 v11, v123
	v_mov_b32_e32 v10, v123
	v_mov_b32_e32 v9, v123
	v_mov_b32_e32 v8, v123
	v_mov_b32_e32 v3, v123
	v_mov_b32_e32 v2, v123
	v_mov_b32_e32 v1, v123
	v_mov_b32_e32 v0, v123
	v_mov_b32_e32 v63, v123
	v_mov_b32_e32 v62, v123
	v_mov_b32_e32 v61, v123
	v_mov_b32_e32 v60, v123
	v_mov_b32_e32 v55, v123
	v_mov_b32_e32 v54, v123
	v_mov_b32_e32 v53, v123
	v_mov_b32_e32 v52, v123
	v_mov_b32_e32 v47, v123
	v_mov_b32_e32 v46, v123
	v_mov_b32_e32 v45, v123
	v_mov_b32_e32 v44, v123
	v_mov_b32_e32 v39, v123
	v_mov_b32_e32 v38, v123
	v_mov_b32_e32 v37, v123
	v_mov_b32_e32 v36, v123
	v_mov_b32_e32 v31, v123
	v_mov_b32_e32 v30, v123
	v_mov_b32_e32 v29, v123
	v_mov_b32_e32 v28, v123
	v_mov_b32_e32 v23, v123
	v_mov_b32_e32 v22, v123
	v_mov_b32_e32 v21, v123
	v_mov_b32_e32 v20, v123
	v_mov_b32_e32 v15, v123
	v_mov_b32_e32 v14, v123
	v_mov_b32_e32 v13, v123
	v_mov_b32_e32 v12, v123
	v_mov_b32_e32 v7, v123
	v_mov_b32_e32 v6, v123
	v_mov_b32_e32 v5, v123
	v_mov_b32_e32 v4, v123
	s_cbranch_vccnz .LBB0_223
	s_and_b64 s[4:5], s[0:1], exec
	s_cselect_b32 s95, s89, s7
	s_cselect_b32 vcc_lo, s90, s6
	s_add_i32 vcc_hi, s7, 0x80080
	s_addk_i32 s6, 0x100
	s_mov_b32 s7, 0
	v_mov_b32_e32 v4, 0
	v_mov_b32_e32 v5, 0
	v_mov_b32_e32 v6, 0
	v_mov_b32_e32 v7, 0
	v_mov_b32_e32 v12, 0
	v_mov_b32_e32 v13, 0
	v_mov_b32_e32 v14, 0
	v_mov_b32_e32 v15, 0
	v_mov_b32_e32 v20, 0
	v_mov_b32_e32 v21, 0
	v_mov_b32_e32 v22, 0
	v_mov_b32_e32 v23, 0
	v_mov_b32_e32 v28, 0
	v_mov_b32_e32 v29, 0
	v_mov_b32_e32 v30, 0
	v_mov_b32_e32 v31, 0
	v_mov_b32_e32 v36, 0
	v_mov_b32_e32 v37, 0
	v_mov_b32_e32 v38, 0
	v_mov_b32_e32 v39, 0
	v_mov_b32_e32 v44, 0
	v_mov_b32_e32 v45, 0
	v_mov_b32_e32 v46, 0
	v_mov_b32_e32 v47, 0
	v_mov_b32_e32 v52, 0
	v_mov_b32_e32 v53, 0
	v_mov_b32_e32 v54, 0
	v_mov_b32_e32 v55, 0
	v_mov_b32_e32 v60, 0
	v_mov_b32_e32 v61, 0
	v_mov_b32_e32 v62, 0
	v_mov_b32_e32 v63, 0
	v_mov_b32_e32 v0, 0
	v_mov_b32_e32 v1, 0
	v_mov_b32_e32 v2, 0
	v_mov_b32_e32 v3, 0
	v_mov_b32_e32 v8, 0
	v_mov_b32_e32 v9, 0
	v_mov_b32_e32 v10, 0
	v_mov_b32_e32 v11, 0
	v_mov_b32_e32 v16, 0
	v_mov_b32_e32 v17, 0
	v_mov_b32_e32 v18, 0
	v_mov_b32_e32 v19, 0
	v_mov_b32_e32 v24, 0
	v_mov_b32_e32 v25, 0
	v_mov_b32_e32 v26, 0
	v_mov_b32_e32 v27, 0
	v_mov_b32_e32 v32, 0
	v_mov_b32_e32 v33, 0
	v_mov_b32_e32 v34, 0
	v_mov_b32_e32 v35, 0
	v_mov_b32_e32 v40, 0
	v_mov_b32_e32 v41, 0
	v_mov_b32_e32 v42, 0
	v_mov_b32_e32 v43, 0
	v_mov_b32_e32 v48, 0
	v_mov_b32_e32 v49, 0
	v_mov_b32_e32 v50, 0
	v_mov_b32_e32 v51, 0
	v_mov_b32_e32 v56, 0
	v_mov_b32_e32 v57, 0
	v_mov_b32_e32 v58, 0
	v_mov_b32_e32 v59, 0
	v_mov_b32_e32 v68, 0
	v_mov_b32_e32 v69, 0
	v_mov_b32_e32 v70, 0
	v_mov_b32_e32 v71, 0
	v_mov_b32_e32 v76, 0
	v_mov_b32_e32 v77, 0
	v_mov_b32_e32 v78, 0
	v_mov_b32_e32 v79, 0
	v_mov_b32_e32 v84, 0
	v_mov_b32_e32 v85, 0
	v_mov_b32_e32 v86, 0
	v_mov_b32_e32 v87, 0
	v_mov_b32_e32 v92, 0
	v_mov_b32_e32 v93, 0
	v_mov_b32_e32 v94, 0
	v_mov_b32_e32 v95, 0
	v_mov_b32_e32 v100, 0
	v_mov_b32_e32 v101, 0
	v_mov_b32_e32 v102, 0
	v_mov_b32_e32 v103, 0
	v_mov_b32_e32 v108, 0
	v_mov_b32_e32 v109, 0
	v_mov_b32_e32 v110, 0
	v_mov_b32_e32 v111, 0
	v_mov_b32_e32 v116, 0
	v_mov_b32_e32 v117, 0
	v_mov_b32_e32 v118, 0
	v_mov_b32_e32 v119, 0
	v_mov_b32_e32 v124, 0
	v_mov_b32_e32 v125, 0
	v_mov_b32_e32 v126, 0
	v_mov_b32_e32 v127, 0
	v_mov_b32_e32 v64, 0
	v_mov_b32_e32 v65, 0
	v_mov_b32_e32 v66, 0
	v_mov_b32_e32 v67, 0
	v_mov_b32_e32 v72, 0
	v_mov_b32_e32 v73, 0
	v_mov_b32_e32 v74, 0
	v_mov_b32_e32 v75, 0
	v_mov_b32_e32 v80, 0
	v_mov_b32_e32 v81, 0
	v_mov_b32_e32 v82, 0
	v_mov_b32_e32 v83, 0
	v_mov_b32_e32 v88, 0
	v_mov_b32_e32 v89, 0
	v_mov_b32_e32 v90, 0
	v_mov_b32_e32 v91, 0
	v_mov_b32_e32 v96, 0
	v_mov_b32_e32 v97, 0
	v_mov_b32_e32 v98, 0
	v_mov_b32_e32 v99, 0
	v_mov_b32_e32 v104, 0
	v_mov_b32_e32 v105, 0
	v_mov_b32_e32 v106, 0
	v_mov_b32_e32 v107, 0
	v_mov_b32_e32 v112, 0
	v_mov_b32_e32 v113, 0
	v_mov_b32_e32 v114, 0
	v_mov_b32_e32 v115, 0
	v_mov_b32_e32 v120, 0
	v_mov_b32_e32 v121, 0
	v_mov_b32_e32 v122, 0
	v_mov_b32_e32 v123, 0

.LBB0_225:
	v_mbcnt_lo_u32_b32 v134, -1, 0
	v_mbcnt_hi_u32_b32 v134, -1, v134
	s_lshl_b32 s5, s94, 7
	v_ashrrev_i32_e32 v132, 1, v134
	s_or_b32 s5, s5, s59
	v_and_b32_e32 v132, -8, v132
	v_add_u32_e32 v132, s5, v132
	v_ashrrev_i32_e32 v133, 31, v132
	v_lshlrev_b64 v[136:137], 2, v[132:133]
	v_lshl_add_u64 v[138:139], s[64:65], 0, v[136:137]
	v_lshl_add_u64 v[136:137], s[22:23], 0, v[136:137]
	s_lshl_b32 s4, s91, 8
	v_mov_b32_e32 v164, v220
	v_mov_b32_e32 v165, v221
	v_mov_b32_e32 v166, v222
	v_mov_b32_e32 v167, v223
	v_mov_b32_e32 v160, v216
	v_mov_b32_e32 v161, v217
	v_mov_b32_e32 v162, v218
	v_mov_b32_e32 v163, v219
	v_mov_b32_e32 v168, v228
	v_mov_b32_e32 v169, v229
	v_mov_b32_e32 v170, v230
	v_mov_b32_e32 v171, v231
	v_mov_b32_e32 v172, v224
	v_mov_b32_e32 v173, v225
	v_mov_b32_e32 v174, v226
	v_mov_b32_e32 v175, v227
	s_add_i32 s4, s4, s58
	v_and_or_b32 v136, v134, 15, s4
	v_ashrrev_i32_e32 v137, 31, v136
	v_lshl_add_u64 v[138:139], v[136:137], 2, s[10:11]
	v_mov_b32_e32 v158, v232
	v_mov_b32_e32 v152, v233
	v_mov_b32_e32 v150, v234
	v_mov_b32_e32 v148, v235
	v_mov_b32_e32 v146, v236
	v_mov_b32_e32 v144, v237
	v_mov_b32_e32 v142, v238
	v_mov_b32_e32 v134, v239
	v_cvt_f32_i32_e32 v141, v124
	v_cvt_f32_i32_e32 v140, v120
	v_cvt_f32_i32_e32 v125, v125
	v_cvt_f32_i32_e32 v124, v121
	v_cvt_f32_i32_e32 v127, v127
	v_cvt_f32_i32_e32 v117, v117
	v_cvt_f32_i32_e32 v119, v119
	v_readlane_b32 s4, v254, 37
	v_readlane_b32 s5, v254, 38
	v_add_u32_e32 v137, 0x80, v136
	v_mov_b32_e32 v138, v160
	v_mov_b32_e32 v139, v172
	v_pk_mul_f32 v[138:139], v[138:139], s[54:55]
	v_mov_b32_e32 v172, v161
	v_pk_mul_f32 v[154:155], v[138:139], v[158:159] op_sel_hi:[1,0]
	s_nop 0
	v_pk_mul_f32 v[154:155], v[154:155], v[140:141]
	v_pk_mul_f32 v[140:141], v[172:173], s[54:55]
	s_nop 0
	v_pk_mul_f32 v[120:121], v[140:141], v[158:159] op_sel_hi:[1,0]
	s_nop 0
	v_pk_mul_f32 v[156:157], v[120:121], v[124:125]
	v_cvt_f32_i32_e32 v125, v126
	v_cvt_f32_i32_e32 v124, v122
	v_mov_b32_e32 v120, v162
	v_mov_b32_e32 v121, v174
	v_pk_mul_f32 v[120:121], v[120:121], s[54:55]
	v_cvt_f32_i32_e32 v126, v123
	v_pk_mul_f32 v[160:161], v[120:121], v[158:159] op_sel_hi:[1,0]
	v_mov_b32_e32 v174, v163
	v_pk_mul_f32 v[160:161], v[160:161], v[124:125]
	v_pk_mul_f32 v[124:125], v[174:175], s[54:55]
	s_nop 0
	v_pk_mul_f32 v[122:123], v[124:125], v[158:159] op_sel_hi:[1,0]
	s_nop 0
	v_pk_mul_f32 v[162:163], v[122:123], v[126:127]
	v_cvt_f32_i32_e32 v127, v116
	v_cvt_f32_i32_e32 v126, v112
	v_mov_b32_e32 v122, v164
	v_mov_b32_e32 v123, v168
	v_pk_mul_f32 v[122:123], v[122:123], s[54:55]
	v_cvt_f32_i32_e32 v116, v113
	v_pk_mul_f32 v[172:173], v[122:123], v[158:159] op_sel_hi:[1,0]
	v_mov_b32_e32 v168, v165
	v_pk_mul_f32 v[172:173], v[172:173], v[126:127]
	v_pk_mul_f32 v[126:127], v[168:169], s[54:55]
	s_nop 0
	v_pk_mul_f32 v[112:113], v[126:127], v[158:159] op_sel_hi:[1,0]
	s_nop 0
	v_pk_mul_f32 v[164:165], v[112:113], v[116:117]
	v_cvt_f32_i32_e32 v117, v118
	v_cvt_f32_i32_e32 v116, v114
	v_mov_b32_e32 v112, v166
	v_mov_b32_e32 v113, v170
	v_pk_mul_f32 v[112:113], v[112:113], s[54:55]
	v_cvt_f32_i32_e32 v118, v115
	v_pk_mul_f32 v[168:169], v[112:113], v[158:159] op_sel_hi:[1,0]
	v_mov_b32_e32 v170, v167
	v_pk_mul_f32 v[168:169], v[168:169], v[116:117]
	v_pk_mul_f32 v[116:117], v[170:171], s[54:55]
	v_mul_f32_e32 v166, 0xbfb8aa3b, v162
	v_pk_mul_f32 v[114:115], v[116:117], v[158:159] op_sel_hi:[1,0]
	v_mul_f32_e32 v158, 0xbfb8aa3b, v160
	v_pk_mul_f32 v[114:115], v[114:115], v[118:119]
	v_mul_f32_e32 v118, 0xbfb8aa3b, v154
	v_mul_f32_e32 v119, 0xbfb8aa3b, v156
	v_exp_f32_e32 v118, v118
	v_exp_f32_e32 v119, v119
	v_exp_f32_e32 v158, v158
	v_exp_f32_e32 v166, v166
	v_mul_f32_e32 v167, 0xbfb8aa3b, v172
	v_mul_f32_e32 v170, 0xbfb8aa3b, v164
	v_mul_f32_e32 v174, 0xbfb8aa3b, v114
	v_mul_f32_e32 v114, v114, v115
	v_add_f32_e32 v115, 1.0, v118
	v_add_f32_e32 v118, 1.0, v119
	v_exp_f32_e32 v167, v167
	v_exp_f32_e32 v170, v170
	v_rcp_f32_e32 v115, v115
	v_rcp_f32_e32 v118, v118
	v_add_f32_e32 v119, 1.0, v158
	v_add_f32_e32 v158, 1.0, v166
	v_rcp_f32_e32 v158, v158
	v_mul_f32_e32 v171, 0xbfb8aa3b, v168
	v_mul_f32_e32 v154, v154, v155
	v_mul_f32_e32 v155, v156, v157
	v_exp_f32_e32 v171, v171
	v_exp_f32_e32 v174, v174
	v_mul_f32_e32 v156, v160, v161
	v_mul_f32_e32 v157, v162, v163
	v_mul_f32_e32 v161, v164, v165
	v_rcp_f32_e32 v119, v119
	v_add_f32_e32 v163, 1.0, v167
	v_add_f32_e32 v164, 1.0, v170
	v_mul_f32_e32 v115, v154, v115
	v_mul_f32_e32 v118, v155, v118
	v_rcp_f32_e32 v163, v163
	v_rcp_f32_e32 v164, v164
	v_mul_f32_e32 v154, v157, v158
	v_med3_f32 v115, v115, s81, v159
	v_med3_f32 v158, v118, s81, v159
	v_mov_b32_e32 v118, 0
	v_cvt_pk_fp8_f32 v118, v115, v158
	v_mul_f32_e32 v160, v172, v173
	v_add_f32_e32 v165, 1.0, v171
	v_add_f32_e32 v166, 1.0, v174
	v_mul_f32_e32 v119, v156, v119
	v_rcp_f32_e32 v165, v165
	v_rcp_f32_e32 v166, v166
	v_mul_f32_e32 v155, v160, v163
	v_mul_f32_e32 v156, v161, v164
	v_med3_f32 v115, v119, s81, v159
	v_med3_f32 v119, v154, s81, v159
	v_cvt_pk_fp8_f32 v118, v115, v119 op_sel:[0,0,1]
	v_med3_f32 v115, v155, s81, v159
	v_med3_f32 v154, v156, s81, v159
	v_mov_b32_e32 v119, 0
	v_cvt_pk_fp8_f32 v119, v115, v154
	v_mul_f32_e32 v162, v168, v169
	v_mul_f32_e32 v157, v162, v165
	v_mul_f32_e32 v114, v114, v166
	v_med3_f32 v115, v157, s81, v159
	v_med3_f32 v114, v114, s81, v159
	v_cvt_pk_fp8_f32 v119, v115, v114 op_sel:[0,0,1]
	v_mov_b64_e32 v[114:115], s[4:5]
	v_mad_i64_i32 v[154:155], s[4:5], v136, s82, v[114:115]
	v_lshl_add_u64 v[154:155], v[154:155], 0, v[132:133]
	global_store_dwordx2 v[154:155], v[118:119], off
	v_cvt_f32_i32_e32 v119, v108
	v_cvt_f32_i32_e32 v118, v104
	v_cvt_f32_i32_e32 v109, v109
	v_cvt_f32_i32_e32 v108, v105
	v_pk_mul_f32 v[104:105], v[138:139], v[152:153] op_sel_hi:[1,0]
	v_cvt_f32_i32_e32 v111, v111
	v_pk_mul_f32 v[104:105], v[104:105], v[118:119]
	v_pk_mul_f32 v[118:119], v[140:141], v[152:153] op_sel_hi:[1,0]
	v_cvt_f32_i32_e32 v101, v101
	v_pk_mul_f32 v[108:109], v[118:119], v[108:109]
	v_cvt_f32_i32_e32 v119, v110
	v_cvt_f32_i32_e32 v118, v106
	v_cvt_f32_i32_e32 v110, v107
	v_pk_mul_f32 v[106:107], v[120:121], v[152:153] op_sel_hi:[1,0]
	v_cvt_f32_i32_e32 v103, v103
	v_pk_mul_f32 v[106:107], v[106:107], v[118:119]
	v_pk_mul_f32 v[118:119], v[124:125], v[152:153] op_sel_hi:[1,0]
	v_or_b32_e32 v154, 16, v136
	v_pk_mul_f32 v[110:111], v[118:119], v[110:111]
	v_cvt_f32_i32_e32 v119, v100
	v_cvt_f32_i32_e32 v118, v96
	v_cvt_f32_i32_e32 v100, v97
	v_pk_mul_f32 v[96:97], v[122:123], v[152:153] op_sel_hi:[1,0]
	v_mul_f32_e32 v155, 0xbfb8aa3b, v110
	v_pk_mul_f32 v[96:97], v[96:97], v[118:119]
	v_pk_mul_f32 v[118:119], v[126:127], v[152:153] op_sel_hi:[1,0]
	v_mul_f32_e32 v156, 0xbfb8aa3b, v96
	v_pk_mul_f32 v[100:101], v[118:119], v[100:101]
	v_cvt_f32_i32_e32 v119, v102
	v_cvt_f32_i32_e32 v118, v98
	v_cvt_f32_i32_e32 v102, v99
	v_pk_mul_f32 v[98:99], v[112:113], v[152:153] op_sel_hi:[1,0]
	v_mul_f32_e32 v157, 0xbfb8aa3b, v100
	v_pk_mul_f32 v[98:99], v[98:99], v[118:119]
	v_pk_mul_f32 v[118:119], v[116:117], v[152:153] op_sel_hi:[1,0]
	v_mul_f32_e32 v152, 0xbfb8aa3b, v106
	v_pk_mul_f32 v[102:103], v[118:119], v[102:103]
	v_mul_f32_e32 v118, 0xbfb8aa3b, v104
	v_mul_f32_e32 v119, 0xbfb8aa3b, v108
	v_exp_f32_e32 v118, v118
	v_exp_f32_e32 v119, v119
	v_exp_f32_e32 v152, v152
	v_exp_f32_e32 v155, v155
	v_exp_f32_e32 v156, v156
	v_exp_f32_e32 v157, v157
	v_mul_f32_e32 v158, 0xbfb8aa3b, v98
	v_mul_f32_e32 v160, 0xbfb8aa3b, v102
	v_mul_f32_e32 v96, v96, v97
	v_mul_f32_e32 v97, v100, v101
	v_add_f32_e32 v100, 1.0, v118
	v_add_f32_e32 v101, 1.0, v119
	v_exp_f32_e32 v158, v158
	v_exp_f32_e32 v160, v160
	v_mul_f32_e32 v104, v104, v105
	v_mul_f32_e32 v105, v108, v109
	v_mul_f32_e32 v98, v98, v99
	v_mul_f32_e32 v99, v102, v103
	v_rcp_f32_e32 v100, v100
	v_rcp_f32_e32 v101, v101
	v_add_f32_e32 v102, 1.0, v152
	v_add_f32_e32 v103, 1.0, v155
	v_add_f32_e32 v108, 1.0, v156
	v_add_f32_e32 v109, 1.0, v157
	v_rcp_f32_e32 v102, v102
	v_rcp_f32_e32 v103, v103
	v_rcp_f32_e32 v108, v108
	v_rcp_f32_e32 v109, v109
	v_mul_f32_e32 v106, v106, v107
	v_mul_f32_e32 v107, v110, v111
	v_add_f32_e32 v110, 1.0, v158
	v_add_f32_e32 v111, 1.0, v160
	v_mul_f32_e32 v100, v104, v100
	v_mul_f32_e32 v101, v105, v101
	v_rcp_f32_e32 v110, v110
	v_rcp_f32_e32 v111, v111
	v_mul_f32_e32 v102, v106, v102
	v_mul_f32_e32 v103, v107, v103
	v_mul_f32_e32 v104, v96, v108
	v_mul_f32_e32 v97, v97, v109
	v_med3_f32 v100, v100, s81, v159
	v_med3_f32 v101, v101, s81, v159
	v_mov_b32_e32 v96, 0
	v_cvt_pk_fp8_f32 v96, v100, v101
	v_med3_f32 v100, v102, s81, v159
	v_med3_f32 v101, v103, s81, v159
	v_med3_f32 v102, v104, s81, v159
	v_med3_f32 v103, v97, s81, v159
	v_mov_b32_e32 v97, 0
	v_cvt_pk_fp8_f32 v97, v102, v103
	v_mul_f32_e32 v98, v98, v110
	v_mul_f32_e32 v99, v99, v111
	v_med3_f32 v98, v98, s81, v159
	v_med3_f32 v99, v99, s81, v159
	v_cvt_pk_fp8_f32 v96, v100, v101 op_sel:[0,0,1]
	v_cvt_pk_fp8_f32 v97, v98, v99 op_sel:[0,0,1]
	v_mad_i64_i32 v[98:99], s[4:5], v154, s82, v[114:115]
	v_lshl_add_u64 v[98:99], v[98:99], 0, v[132:133]
	global_store_dwordx2 v[98:99], v[96:97], off
	v_cvt_f32_i32_e32 v97, v92
	v_cvt_f32_i32_e32 v96, v88
	v_cvt_f32_i32_e32 v93, v93
	v_cvt_f32_i32_e32 v92, v89
	v_pk_mul_f32 v[88:89], v[138:139], v[150:151] op_sel_hi:[1,0]
	v_cvt_f32_i32_e32 v95, v95
	v_pk_mul_f32 v[88:89], v[88:89], v[96:97]
	v_pk_mul_f32 v[96:97], v[140:141], v[150:151] op_sel_hi:[1,0]
	v_cvt_f32_i32_e32 v85, v85
	v_pk_mul_f32 v[92:93], v[96:97], v[92:93]
	v_cvt_f32_i32_e32 v97, v94
	v_cvt_f32_i32_e32 v96, v90
	v_cvt_f32_i32_e32 v94, v91
	v_pk_mul_f32 v[90:91], v[120:121], v[150:151] op_sel_hi:[1,0]
	v_cvt_f32_i32_e32 v87, v87
	v_pk_mul_f32 v[90:91], v[90:91], v[96:97]
	v_pk_mul_f32 v[96:97], v[124:125], v[150:151] op_sel_hi:[1,0]
	v_mul_f32_e32 v99, 0xbfb8aa3b, v90
	v_pk_mul_f32 v[94:95], v[96:97], v[94:95]
	v_cvt_f32_i32_e32 v97, v84
	v_cvt_f32_i32_e32 v96, v80
	v_cvt_f32_i32_e32 v84, v81
	v_pk_mul_f32 v[80:81], v[122:123], v[150:151] op_sel_hi:[1,0]
	v_mul_f32_e32 v100, 0xbfb8aa3b, v94
	v_pk_mul_f32 v[80:81], v[80:81], v[96:97]
	v_pk_mul_f32 v[96:97], v[126:127], v[150:151] op_sel_hi:[1,0]
	v_mul_f32_e32 v101, 0xbfb8aa3b, v80
	v_pk_mul_f32 v[84:85], v[96:97], v[84:85]
	v_cvt_f32_i32_e32 v97, v86
	v_cvt_f32_i32_e32 v96, v82
	v_cvt_f32_i32_e32 v86, v83
	v_pk_mul_f32 v[82:83], v[112:113], v[150:151] op_sel_hi:[1,0]
	v_mul_f32_e32 v102, 0xbfb8aa3b, v84
	v_pk_mul_f32 v[82:83], v[82:83], v[96:97]
	v_pk_mul_f32 v[96:97], v[116:117], v[150:151] op_sel_hi:[1,0]
	v_exp_f32_e32 v99, v99
	v_pk_mul_f32 v[86:87], v[96:97], v[86:87]
	v_mul_f32_e32 v96, 0xbfb8aa3b, v88
	v_mul_f32_e32 v97, 0xbfb8aa3b, v92
	v_exp_f32_e32 v96, v96
	v_exp_f32_e32 v97, v97
	v_exp_f32_e32 v100, v100
	v_exp_f32_e32 v101, v101
	v_exp_f32_e32 v102, v102
	v_mul_f32_e32 v103, 0xbfb8aa3b, v82
	v_mul_f32_e32 v104, 0xbfb8aa3b, v86
	v_mul_f32_e32 v80, v80, v81
	v_mul_f32_e32 v81, v84, v85
	v_add_f32_e32 v84, 1.0, v96
	v_add_f32_e32 v85, 1.0, v97
	v_exp_f32_e32 v103, v103
	v_exp_f32_e32 v104, v104
	v_mul_f32_e32 v88, v88, v89
	v_mul_f32_e32 v89, v92, v93
	v_mul_f32_e32 v82, v82, v83
	v_mul_f32_e32 v83, v86, v87
	v_rcp_f32_e32 v84, v84
	v_rcp_f32_e32 v85, v85
	v_add_f32_e32 v86, 1.0, v99
	v_add_f32_e32 v87, 1.0, v100
	v_add_f32_e32 v92, 1.0, v101
	v_add_f32_e32 v93, 1.0, v102
	v_rcp_f32_e32 v86, v86
	v_rcp_f32_e32 v87, v87
	v_rcp_f32_e32 v92, v92
	v_rcp_f32_e32 v93, v93
	v_mul_f32_e32 v90, v90, v91
	v_mul_f32_e32 v91, v94, v95
	v_add_f32_e32 v94, 1.0, v103
	v_add_f32_e32 v95, 1.0, v104
	v_mul_f32_e32 v84, v88, v84
	v_mul_f32_e32 v85, v89, v85
	v_rcp_f32_e32 v94, v94
	v_rcp_f32_e32 v95, v95
	v_mul_f32_e32 v86, v90, v86
	v_mul_f32_e32 v87, v91, v87
	v_mul_f32_e32 v88, v80, v92
	v_mul_f32_e32 v81, v81, v93
	v_med3_f32 v84, v84, s81, v159
	v_med3_f32 v85, v85, s81, v159
	v_mov_b32_e32 v80, 0
	v_cvt_pk_fp8_f32 v80, v84, v85
	v_med3_f32 v84, v86, s81, v159
	v_med3_f32 v85, v87, s81, v159
	v_med3_f32 v86, v88, s81, v159
	v_med3_f32 v87, v81, s81, v159
	v_mov_b32_e32 v81, 0
	v_cvt_pk_fp8_f32 v81, v86, v87
	v_mul_f32_e32 v82, v82, v94
	v_mul_f32_e32 v83, v83, v95
	v_med3_f32 v82, v82, s81, v159
	v_med3_f32 v83, v83, s81, v159
	v_cvt_pk_fp8_f32 v80, v84, v85 op_sel:[0,0,1]
	v_cvt_pk_fp8_f32 v81, v82, v83 op_sel:[0,0,1]
	v_or_b32_e32 v98, 32, v136
	v_mad_i64_i32 v[82:83], s[4:5], v98, s82, v[114:115]
	v_lshl_add_u64 v[82:83], v[82:83], 0, v[132:133]
	global_store_dwordx2 v[82:83], v[80:81], off
	v_cvt_f32_i32_e32 v81, v76
	v_cvt_f32_i32_e32 v80, v72
	v_cvt_f32_i32_e32 v77, v77
	v_cvt_f32_i32_e32 v76, v73
	v_pk_mul_f32 v[72:73], v[138:139], v[148:149] op_sel_hi:[1,0]
	v_cvt_f32_i32_e32 v79, v79
	v_pk_mul_f32 v[72:73], v[72:73], v[80:81]
	v_pk_mul_f32 v[80:81], v[140:141], v[148:149] op_sel_hi:[1,0]
	v_cvt_f32_i32_e32 v69, v69
	v_pk_mul_f32 v[76:77], v[80:81], v[76:77]
	v_cvt_f32_i32_e32 v81, v78
	v_cvt_f32_i32_e32 v80, v74
	v_cvt_f32_i32_e32 v78, v75
	v_pk_mul_f32 v[74:75], v[120:121], v[148:149] op_sel_hi:[1,0]
	v_cvt_f32_i32_e32 v71, v71
	v_pk_mul_f32 v[74:75], v[74:75], v[80:81]
	v_pk_mul_f32 v[80:81], v[124:125], v[148:149] op_sel_hi:[1,0]
	v_mul_f32_e32 v83, 0xbfb8aa3b, v74
	v_pk_mul_f32 v[78:79], v[80:81], v[78:79]
	v_cvt_f32_i32_e32 v81, v68
	v_cvt_f32_i32_e32 v80, v64
	v_cvt_f32_i32_e32 v68, v65
	v_pk_mul_f32 v[64:65], v[122:123], v[148:149] op_sel_hi:[1,0]
	v_mul_f32_e32 v84, 0xbfb8aa3b, v78
	v_pk_mul_f32 v[64:65], v[64:65], v[80:81]
	v_pk_mul_f32 v[80:81], v[126:127], v[148:149] op_sel_hi:[1,0]
	v_mul_f32_e32 v85, 0xbfb8aa3b, v64
	v_pk_mul_f32 v[68:69], v[80:81], v[68:69]
	v_cvt_f32_i32_e32 v81, v70
	v_cvt_f32_i32_e32 v80, v66
	v_cvt_f32_i32_e32 v70, v67
	v_pk_mul_f32 v[66:67], v[112:113], v[148:149] op_sel_hi:[1,0]
	v_mul_f32_e32 v86, 0xbfb8aa3b, v68
	v_pk_mul_f32 v[66:67], v[66:67], v[80:81]
	v_pk_mul_f32 v[80:81], v[116:117], v[148:149] op_sel_hi:[1,0]
	v_exp_f32_e32 v83, v83
	v_pk_mul_f32 v[70:71], v[80:81], v[70:71]
	v_mul_f32_e32 v80, 0xbfb8aa3b, v72
	v_mul_f32_e32 v81, 0xbfb8aa3b, v76
	v_exp_f32_e32 v80, v80
	v_exp_f32_e32 v81, v81
	v_exp_f32_e32 v84, v84
	v_exp_f32_e32 v85, v85
	v_exp_f32_e32 v86, v86
	v_mul_f32_e32 v87, 0xbfb8aa3b, v66
	v_mul_f32_e32 v88, 0xbfb8aa3b, v70
	v_mul_f32_e32 v64, v64, v65
	v_mul_f32_e32 v65, v68, v69
	v_add_f32_e32 v68, 1.0, v80
	v_add_f32_e32 v69, 1.0, v81
	v_exp_f32_e32 v87, v87
	v_exp_f32_e32 v88, v88
	v_mul_f32_e32 v72, v72, v73
	v_mul_f32_e32 v73, v76, v77
	v_mul_f32_e32 v66, v66, v67
	v_mul_f32_e32 v67, v70, v71
	v_rcp_f32_e32 v68, v68
	v_rcp_f32_e32 v69, v69
	v_add_f32_e32 v70, 1.0, v83
	v_add_f32_e32 v71, 1.0, v84
	v_add_f32_e32 v76, 1.0, v85
	v_add_f32_e32 v77, 1.0, v86
	v_rcp_f32_e32 v70, v70
	v_rcp_f32_e32 v71, v71
	v_rcp_f32_e32 v76, v76
	v_rcp_f32_e32 v77, v77
	v_mul_f32_e32 v74, v74, v75
	v_mul_f32_e32 v75, v78, v79
	v_add_f32_e32 v78, 1.0, v87
	v_add_f32_e32 v79, 1.0, v88
	v_mul_f32_e32 v68, v72, v68
	v_mul_f32_e32 v69, v73, v69
	v_rcp_f32_e32 v78, v78
	v_rcp_f32_e32 v79, v79
	v_mul_f32_e32 v70, v74, v70
	v_mul_f32_e32 v71, v75, v71
	v_mul_f32_e32 v72, v64, v76
	v_mul_f32_e32 v65, v65, v77
	v_med3_f32 v68, v68, s81, v159
	v_med3_f32 v69, v69, s81, v159
	v_mov_b32_e32 v64, 0
	v_cvt_pk_fp8_f32 v64, v68, v69
	v_med3_f32 v68, v70, s81, v159
	v_med3_f32 v69, v71, s81, v159
	v_med3_f32 v70, v72, s81, v159
	v_med3_f32 v71, v65, s81, v159
	v_mov_b32_e32 v65, 0
	v_cvt_pk_fp8_f32 v65, v70, v71
	v_mul_f32_e32 v66, v66, v78
	v_mul_f32_e32 v67, v67, v79
	v_med3_f32 v66, v66, s81, v159
	v_med3_f32 v67, v67, s81, v159
	v_cvt_pk_fp8_f32 v64, v68, v69 op_sel:[0,0,1]
	v_cvt_pk_fp8_f32 v65, v66, v67 op_sel:[0,0,1]
	v_or_b32_e32 v82, 48, v136
	v_mad_i64_i32 v[66:67], s[4:5], v82, s82, v[114:115]
	v_lshl_add_u64 v[66:67], v[66:67], 0, v[132:133]
	global_store_dwordx2 v[66:67], v[64:65], off
	v_cvt_f32_i32_e32 v65, v60
	v_cvt_f32_i32_e32 v64, v56
	v_cvt_f32_i32_e32 v61, v61
	v_cvt_f32_i32_e32 v60, v57
	v_pk_mul_f32 v[56:57], v[138:139], v[146:147] op_sel_hi:[1,0]
	v_cvt_f32_i32_e32 v63, v63
	v_pk_mul_f32 v[56:57], v[56:57], v[64:65]
	v_pk_mul_f32 v[64:65], v[140:141], v[146:147] op_sel_hi:[1,0]
	v_cvt_f32_i32_e32 v53, v53
	v_pk_mul_f32 v[60:61], v[64:65], v[60:61]
	v_cvt_f32_i32_e32 v65, v62
	v_cvt_f32_i32_e32 v64, v58
	v_cvt_f32_i32_e32 v62, v59
	v_pk_mul_f32 v[58:59], v[120:121], v[146:147] op_sel_hi:[1,0]
	v_cvt_f32_i32_e32 v55, v55
	v_pk_mul_f32 v[58:59], v[58:59], v[64:65]
	v_pk_mul_f32 v[64:65], v[124:125], v[146:147] op_sel_hi:[1,0]
	v_mul_f32_e32 v66, 0xbfb8aa3b, v58
	v_pk_mul_f32 v[62:63], v[64:65], v[62:63]
	v_cvt_f32_i32_e32 v65, v52
	v_cvt_f32_i32_e32 v64, v48
	v_cvt_f32_i32_e32 v52, v49
	v_pk_mul_f32 v[48:49], v[122:123], v[146:147] op_sel_hi:[1,0]
	v_mul_f32_e32 v67, 0xbfb8aa3b, v62
	v_pk_mul_f32 v[48:49], v[48:49], v[64:65]
	v_pk_mul_f32 v[64:65], v[126:127], v[146:147] op_sel_hi:[1,0]
	v_mul_f32_e32 v68, 0xbfb8aa3b, v48
	v_pk_mul_f32 v[52:53], v[64:65], v[52:53]
	v_cvt_f32_i32_e32 v65, v54
	v_cvt_f32_i32_e32 v64, v50
	v_cvt_f32_i32_e32 v54, v51
	v_pk_mul_f32 v[50:51], v[112:113], v[146:147] op_sel_hi:[1,0]
	v_mul_f32_e32 v69, 0xbfb8aa3b, v52
	v_pk_mul_f32 v[50:51], v[50:51], v[64:65]
	v_pk_mul_f32 v[64:65], v[116:117], v[146:147] op_sel_hi:[1,0]
	v_exp_f32_e32 v66, v66
	v_pk_mul_f32 v[54:55], v[64:65], v[54:55]
	v_mul_f32_e32 v64, 0xbfb8aa3b, v56
	v_mul_f32_e32 v65, 0xbfb8aa3b, v60
	v_exp_f32_e32 v64, v64
	v_exp_f32_e32 v65, v65
	v_exp_f32_e32 v67, v67
	v_exp_f32_e32 v68, v68
	v_exp_f32_e32 v69, v69
	v_mul_f32_e32 v70, 0xbfb8aa3b, v50
	v_mul_f32_e32 v71, 0xbfb8aa3b, v54
	v_mul_f32_e32 v48, v48, v49
	v_mul_f32_e32 v49, v52, v53
	v_add_f32_e32 v52, 1.0, v64
	v_add_f32_e32 v53, 1.0, v65
	v_exp_f32_e32 v70, v70
	v_exp_f32_e32 v71, v71
	v_mul_f32_e32 v56, v56, v57
	v_mul_f32_e32 v57, v60, v61
	v_mul_f32_e32 v50, v50, v51
	v_mul_f32_e32 v51, v54, v55
	v_rcp_f32_e32 v52, v52
	v_rcp_f32_e32 v53, v53
	v_add_f32_e32 v54, 1.0, v66
	v_add_f32_e32 v55, 1.0, v67
	v_add_f32_e32 v60, 1.0, v68
	v_add_f32_e32 v61, 1.0, v69
	v_rcp_f32_e32 v54, v54
	v_rcp_f32_e32 v55, v55
	v_rcp_f32_e32 v60, v60
	v_rcp_f32_e32 v61, v61
	v_mul_f32_e32 v58, v58, v59
	v_mul_f32_e32 v59, v62, v63
	v_add_f32_e32 v62, 1.0, v70
	v_add_f32_e32 v63, 1.0, v71
	v_mul_f32_e32 v52, v56, v52
	v_mul_f32_e32 v53, v57, v53
	v_rcp_f32_e32 v62, v62
	v_rcp_f32_e32 v63, v63
	v_mul_f32_e32 v54, v58, v54
	v_mul_f32_e32 v55, v59, v55
	v_mul_f32_e32 v56, v48, v60
	v_mul_f32_e32 v49, v49, v61
	v_med3_f32 v52, v52, s81, v159
	v_med3_f32 v53, v53, s81, v159
	v_mov_b32_e32 v48, 0
	v_cvt_pk_fp8_f32 v48, v52, v53
	v_med3_f32 v52, v54, s81, v159
	v_med3_f32 v53, v55, s81, v159
	v_med3_f32 v54, v56, s81, v159
	v_med3_f32 v55, v49, s81, v159
	v_mov_b32_e32 v49, 0
	v_cvt_pk_fp8_f32 v49, v54, v55
	v_mul_f32_e32 v50, v50, v62
	v_mul_f32_e32 v51, v51, v63
	v_med3_f32 v50, v50, s81, v159
	v_med3_f32 v51, v51, s81, v159
	v_cvt_pk_fp8_f32 v48, v52, v53 op_sel:[0,0,1]
	v_cvt_pk_fp8_f32 v49, v50, v51 op_sel:[0,0,1]
	v_mad_i64_i32 v[50:51], s[4:5], v137, s82, v[114:115]
	v_lshl_add_u64 v[50:51], v[50:51], 0, v[132:133]
	global_store_dwordx2 v[50:51], v[48:49], off
	v_cvt_f32_i32_e32 v49, v44
	v_cvt_f32_i32_e32 v48, v40
	v_cvt_f32_i32_e32 v45, v45
	v_cvt_f32_i32_e32 v44, v41
	v_pk_mul_f32 v[40:41], v[138:139], v[144:145] op_sel_hi:[1,0]
	v_cvt_f32_i32_e32 v47, v47
	v_pk_mul_f32 v[40:41], v[40:41], v[48:49]
	v_pk_mul_f32 v[48:49], v[140:141], v[144:145] op_sel_hi:[1,0]
	v_cvt_f32_i32_e32 v37, v37
	v_pk_mul_f32 v[44:45], v[48:49], v[44:45]
	v_cvt_f32_i32_e32 v49, v46
	v_cvt_f32_i32_e32 v48, v42
	v_cvt_f32_i32_e32 v46, v43
	v_pk_mul_f32 v[42:43], v[120:121], v[144:145] op_sel_hi:[1,0]
	v_cvt_f32_i32_e32 v39, v39
	v_pk_mul_f32 v[42:43], v[42:43], v[48:49]
	v_pk_mul_f32 v[48:49], v[124:125], v[144:145] op_sel_hi:[1,0]
	v_mul_f32_e32 v51, 0xbfb8aa3b, v42
	v_pk_mul_f32 v[46:47], v[48:49], v[46:47]
	v_cvt_f32_i32_e32 v49, v36
	v_cvt_f32_i32_e32 v48, v32
	v_cvt_f32_i32_e32 v36, v33
	v_pk_mul_f32 v[32:33], v[122:123], v[144:145] op_sel_hi:[1,0]
	v_mul_f32_e32 v52, 0xbfb8aa3b, v46
	v_pk_mul_f32 v[32:33], v[32:33], v[48:49]
	v_pk_mul_f32 v[48:49], v[126:127], v[144:145] op_sel_hi:[1,0]
	v_mul_f32_e32 v53, 0xbfb8aa3b, v32
	v_pk_mul_f32 v[36:37], v[48:49], v[36:37]
	v_cvt_f32_i32_e32 v49, v38
	v_cvt_f32_i32_e32 v48, v34
	v_cvt_f32_i32_e32 v38, v35
	v_pk_mul_f32 v[34:35], v[112:113], v[144:145] op_sel_hi:[1,0]
	v_mul_f32_e32 v54, 0xbfb8aa3b, v36
	v_pk_mul_f32 v[34:35], v[34:35], v[48:49]
	v_pk_mul_f32 v[48:49], v[116:117], v[144:145] op_sel_hi:[1,0]
	v_exp_f32_e32 v51, v51
	v_pk_mul_f32 v[38:39], v[48:49], v[38:39]
	v_mul_f32_e32 v48, 0xbfb8aa3b, v40
	v_mul_f32_e32 v49, 0xbfb8aa3b, v44
	v_exp_f32_e32 v48, v48
	v_exp_f32_e32 v49, v49
	v_exp_f32_e32 v52, v52
	v_exp_f32_e32 v53, v53
	v_exp_f32_e32 v54, v54
	v_mul_f32_e32 v55, 0xbfb8aa3b, v34
	v_mul_f32_e32 v56, 0xbfb8aa3b, v38
	v_mul_f32_e32 v32, v32, v33
	v_mul_f32_e32 v33, v36, v37
	v_add_f32_e32 v36, 1.0, v48
	v_add_f32_e32 v37, 1.0, v49
	v_exp_f32_e32 v55, v55
	v_exp_f32_e32 v56, v56
	v_mul_f32_e32 v40, v40, v41
	v_mul_f32_e32 v41, v44, v45
	v_mul_f32_e32 v34, v34, v35
	v_mul_f32_e32 v35, v38, v39
	v_rcp_f32_e32 v36, v36
	v_rcp_f32_e32 v37, v37
	v_add_f32_e32 v38, 1.0, v51
	v_add_f32_e32 v39, 1.0, v52
	v_add_f32_e32 v44, 1.0, v53
	v_add_f32_e32 v45, 1.0, v54
	v_rcp_f32_e32 v38, v38
	v_rcp_f32_e32 v39, v39
	v_rcp_f32_e32 v44, v44
	v_rcp_f32_e32 v45, v45
	v_mul_f32_e32 v42, v42, v43
	v_mul_f32_e32 v43, v46, v47
	v_add_f32_e32 v46, 1.0, v55
	v_add_f32_e32 v47, 1.0, v56
	v_mul_f32_e32 v36, v40, v36
	v_mul_f32_e32 v37, v41, v37
	v_rcp_f32_e32 v46, v46
	v_rcp_f32_e32 v47, v47
	v_mul_f32_e32 v38, v42, v38
	v_mul_f32_e32 v39, v43, v39
	v_mul_f32_e32 v40, v32, v44
	v_mul_f32_e32 v33, v33, v45
	v_med3_f32 v36, v36, s81, v159
	v_med3_f32 v37, v37, s81, v159
	v_mov_b32_e32 v32, 0
	v_cvt_pk_fp8_f32 v32, v36, v37
	v_med3_f32 v36, v38, s81, v159
	v_med3_f32 v37, v39, s81, v159
	v_med3_f32 v38, v40, s81, v159
	v_med3_f32 v39, v33, s81, v159
	v_mov_b32_e32 v33, 0
	v_cvt_pk_fp8_f32 v33, v38, v39
	v_mul_f32_e32 v34, v34, v46
	v_mul_f32_e32 v35, v35, v47
	v_med3_f32 v34, v34, s81, v159
	v_med3_f32 v35, v35, s81, v159
	v_cvt_pk_fp8_f32 v32, v36, v37 op_sel:[0,0,1]
	v_cvt_pk_fp8_f32 v33, v34, v35 op_sel:[0,0,1]
	v_add_u32_e32 v50, 0x90, v136
	v_mad_i64_i32 v[34:35], s[4:5], v50, s82, v[114:115]
	v_lshl_add_u64 v[34:35], v[34:35], 0, v[132:133]
	global_store_dwordx2 v[34:35], v[32:33], off
	v_cvt_f32_i32_e32 v33, v28
	v_cvt_f32_i32_e32 v32, v24
	v_cvt_f32_i32_e32 v29, v29
	v_cvt_f32_i32_e32 v28, v25
	v_pk_mul_f32 v[24:25], v[138:139], v[142:143] op_sel_hi:[1,0]
	v_cvt_f32_i32_e32 v31, v31
	v_pk_mul_f32 v[24:25], v[24:25], v[32:33]
	v_pk_mul_f32 v[32:33], v[140:141], v[142:143] op_sel_hi:[1,0]
	v_cvt_f32_i32_e32 v21, v21
	v_pk_mul_f32 v[28:29], v[32:33], v[28:29]
	v_cvt_f32_i32_e32 v33, v30
	v_cvt_f32_i32_e32 v32, v26
	v_cvt_f32_i32_e32 v30, v27
	v_pk_mul_f32 v[26:27], v[120:121], v[142:143] op_sel_hi:[1,0]
	v_cvt_f32_i32_e32 v23, v23
	v_pk_mul_f32 v[26:27], v[26:27], v[32:33]
	v_pk_mul_f32 v[32:33], v[124:125], v[142:143] op_sel_hi:[1,0]
	v_mul_f32_e32 v35, 0xbfb8aa3b, v26
	v_pk_mul_f32 v[30:31], v[32:33], v[30:31]
	v_cvt_f32_i32_e32 v33, v20
	v_cvt_f32_i32_e32 v32, v16
	v_cvt_f32_i32_e32 v20, v17
	v_pk_mul_f32 v[16:17], v[122:123], v[142:143] op_sel_hi:[1,0]
	v_mul_f32_e32 v36, 0xbfb8aa3b, v30
	v_pk_mul_f32 v[16:17], v[16:17], v[32:33]
	v_pk_mul_f32 v[32:33], v[126:127], v[142:143] op_sel_hi:[1,0]
	v_mul_f32_e32 v37, 0xbfb8aa3b, v16
	v_pk_mul_f32 v[20:21], v[32:33], v[20:21]
	v_cvt_f32_i32_e32 v33, v22
	v_cvt_f32_i32_e32 v32, v18
	v_cvt_f32_i32_e32 v22, v19
	v_pk_mul_f32 v[18:19], v[112:113], v[142:143] op_sel_hi:[1,0]
	v_mul_f32_e32 v38, 0xbfb8aa3b, v20
	v_pk_mul_f32 v[18:19], v[18:19], v[32:33]
	v_pk_mul_f32 v[32:33], v[116:117], v[142:143] op_sel_hi:[1,0]
	v_exp_f32_e32 v35, v35
	v_pk_mul_f32 v[22:23], v[32:33], v[22:23]
	v_mul_f32_e32 v32, 0xbfb8aa3b, v24
	v_mul_f32_e32 v33, 0xbfb8aa3b, v28
	v_exp_f32_e32 v32, v32
	v_exp_f32_e32 v33, v33
	v_exp_f32_e32 v36, v36
	v_exp_f32_e32 v37, v37
	v_exp_f32_e32 v38, v38
	v_mul_f32_e32 v39, 0xbfb8aa3b, v18
	v_mul_f32_e32 v40, 0xbfb8aa3b, v22
	v_mul_f32_e32 v16, v16, v17
	v_mul_f32_e32 v17, v20, v21
	v_add_f32_e32 v20, 1.0, v32
	v_add_f32_e32 v21, 1.0, v33
	v_exp_f32_e32 v39, v39
	v_exp_f32_e32 v40, v40
	v_mul_f32_e32 v24, v24, v25
	v_mul_f32_e32 v25, v28, v29
	v_mul_f32_e32 v18, v18, v19
	v_mul_f32_e32 v19, v22, v23
	v_rcp_f32_e32 v20, v20
	v_rcp_f32_e32 v21, v21
	v_add_f32_e32 v22, 1.0, v35
	v_add_f32_e32 v23, 1.0, v36
	v_add_f32_e32 v28, 1.0, v37
	v_add_f32_e32 v29, 1.0, v38
	v_rcp_f32_e32 v22, v22
	v_rcp_f32_e32 v23, v23
	v_rcp_f32_e32 v28, v28
	v_rcp_f32_e32 v29, v29
	v_mul_f32_e32 v26, v26, v27
	v_mul_f32_e32 v27, v30, v31
	v_add_f32_e32 v30, 1.0, v39
	v_add_f32_e32 v31, 1.0, v40
	v_mul_f32_e32 v20, v24, v20
	v_mul_f32_e32 v21, v25, v21
	v_rcp_f32_e32 v30, v30
	v_rcp_f32_e32 v31, v31
	v_mul_f32_e32 v22, v26, v22
	v_mul_f32_e32 v23, v27, v23
	v_mul_f32_e32 v24, v16, v28
	v_mul_f32_e32 v17, v17, v29
	v_med3_f32 v20, v20, s81, v159
	v_med3_f32 v21, v21, s81, v159
	v_mov_b32_e32 v16, 0
	v_cvt_pk_fp8_f32 v16, v20, v21
	v_med3_f32 v20, v22, s81, v159
	v_med3_f32 v21, v23, s81, v159
	v_med3_f32 v22, v24, s81, v159
	v_med3_f32 v23, v17, s81, v159
	v_mov_b32_e32 v17, 0
	v_cvt_pk_fp8_f32 v17, v22, v23
	v_mul_f32_e32 v18, v18, v30
	v_mul_f32_e32 v19, v19, v31
	v_med3_f32 v18, v18, s81, v159
	v_med3_f32 v19, v19, s81, v159
	v_cvt_pk_fp8_f32 v16, v20, v21 op_sel:[0,0,1]
	v_cvt_pk_fp8_f32 v17, v18, v19 op_sel:[0,0,1]
	v_add_u32_e32 v34, 0xa0, v136
	v_mad_i64_i32 v[18:19], s[4:5], v34, s82, v[114:115]
	v_lshl_add_u64 v[18:19], v[18:19], 0, v[132:133]
	global_store_dwordx2 v[18:19], v[16:17], off
	v_cvt_f32_i32_e32 v17, v12
	v_cvt_f32_i32_e32 v13, v13
	v_cvt_f32_i32_e32 v12, v9
	v_cvt_f32_i32_e32 v16, v8
	v_pk_mul_f32 v[8:9], v[140:141], v[134:135] op_sel_hi:[1,0]
	v_cvt_f32_i32_e32 v15, v15
	v_pk_mul_f32 v[8:9], v[8:9], v[12:13]
	v_cvt_f32_i32_e32 v13, v14
	v_cvt_f32_i32_e32 v14, v11
	v_cvt_f32_i32_e32 v12, v10
	v_pk_mul_f32 v[10:11], v[124:125], v[134:135] op_sel_hi:[1,0]
	v_cvt_f32_i32_e32 v5, v5
	v_pk_mul_f32 v[10:11], v[10:11], v[14:15]
	v_cvt_f32_i32_e32 v15, v4
	v_cvt_f32_i32_e32 v4, v1
	v_cvt_f32_i32_e32 v14, v0
	v_pk_mul_f32 v[0:1], v[126:127], v[134:135] op_sel_hi:[1,0]
	v_pk_mul_f32 v[18:19], v[138:139], v[134:135] op_sel_hi:[1,0]
	v_pk_mul_f32 v[0:1], v[0:1], v[4:5]
	v_cvt_f32_i32_e32 v5, v6
	v_cvt_f32_i32_e32 v4, v2
	v_cvt_f32_i32_e32 v7, v7
	v_cvt_f32_i32_e32 v6, v3
	v_pk_mul_f32 v[16:17], v[18:19], v[16:17]
	v_pk_mul_f32 v[18:19], v[120:121], v[134:135] op_sel_hi:[1,0]
	v_pk_mul_f32 v[2:3], v[116:117], v[134:135] op_sel_hi:[1,0]
	v_pk_mul_f32 v[12:13], v[18:19], v[12:13]
	v_pk_mul_f32 v[18:19], v[122:123], v[134:135] op_sel_hi:[1,0]
	v_pk_mul_f32 v[2:3], v[2:3], v[6:7]
	v_pk_mul_f32 v[14:15], v[18:19], v[14:15]
	v_pk_mul_f32 v[18:19], v[112:113], v[134:135] op_sel_hi:[1,0]
	v_mul_f32_e32 v6, 0xbfb8aa3b, v16
	v_pk_mul_f32 v[4:5], v[18:19], v[4:5]
	v_mul_f32_e32 v7, 0xbfb8aa3b, v8
	v_exp_f32_e32 v6, v6
	v_exp_f32_e32 v7, v7
	v_mul_f32_e32 v18, 0xbfb8aa3b, v12
	v_mul_f32_e32 v22, 0xbfb8aa3b, v0
	v_mul_f32_e32 v23, 0xbfb8aa3b, v4
	v_exp_f32_e32 v18, v18
	v_exp_f32_e32 v22, v22
	v_exp_f32_e32 v23, v23
	v_mul_f32_e32 v19, 0xbfb8aa3b, v10
	v_exp_f32_e32 v19, v19
	v_mul_f32_e32 v21, 0xbfb8aa3b, v14
	v_mul_f32_e32 v24, 0xbfb8aa3b, v2
	v_mul_f32_e32 v0, v0, v1
	v_mul_f32_e32 v1, v4, v5
	v_mul_f32_e32 v2, v2, v3
	v_add_f32_e32 v3, 1.0, v6
	v_add_f32_e32 v4, 1.0, v7
	v_exp_f32_e32 v21, v21
	v_mul_f32_e32 v8, v8, v9
	v_mul_f32_e32 v9, v12, v13
	v_rcp_f32_e32 v3, v3
	v_rcp_f32_e32 v4, v4
	v_add_f32_e32 v5, 1.0, v18
	v_add_f32_e32 v12, 1.0, v22
	v_add_f32_e32 v13, 1.0, v23
	v_rcp_f32_e32 v5, v5
	v_rcp_f32_e32 v12, v12
	v_rcp_f32_e32 v13, v13
	v_mul_f32_e32 v16, v16, v17
	v_add_f32_e32 v6, 1.0, v19
	v_exp_f32_e32 v24, v24
	v_rcp_f32_e32 v6, v6
	v_add_f32_e32 v7, 1.0, v21
	v_mul_f32_e32 v3, v16, v3
	v_mul_f32_e32 v4, v8, v4
	v_rcp_f32_e32 v7, v7
	v_mul_f32_e32 v5, v9, v5
	v_mul_f32_e32 v8, v0, v12
	v_mul_f32_e32 v9, v1, v13
	v_med3_f32 v1, v3, s81, v159
	v_med3_f32 v3, v4, s81, v159
	v_mov_b32_e32 v0, 0
	v_cvt_pk_fp8_f32 v0, v1, v3
	v_mul_f32_e32 v10, v10, v11
	v_mul_f32_e32 v11, v14, v15
	v_add_f32_e32 v14, 1.0, v24
	v_mul_f32_e32 v6, v10, v6
	v_rcp_f32_e32 v14, v14
	v_mul_f32_e32 v7, v11, v7
	v_med3_f32 v1, v5, s81, v159
	v_med3_f32 v3, v6, s81, v159
	v_cvt_pk_fp8_f32 v0, v1, v3 op_sel:[0,0,1]
	v_med3_f32 v3, v7, s81, v159
	v_med3_f32 v4, v8, s81, v159
	v_mov_b32_e32 v1, 0
	v_cvt_pk_fp8_f32 v1, v3, v4
	v_mul_f32_e32 v2, v2, v14
	v_med3_f32 v3, v9, s81, v159
	v_med3_f32 v2, v2, s81, v159
	v_cvt_pk_fp8_f32 v1, v3, v2 op_sel:[0,0,1]
	v_add_u32_e32 v20, 0xb0, v136
	v_mad_i64_i32 v[2:3], s[4:5], v20, s82, v[114:115]
	v_lshl_add_u64 v[2:3], v[2:3], 0, v[132:133]
	global_store_dwordx2 v[2:3], v[0:1], off
	s_andn2_b64 vcc, exec, s[0:1]
	s_mov_b64 s[0:1], -1
	s_cbranch_vccnz .LBB0_212
	s_andn2_b64 vcc, exec, s[46:47]
	s_cbranch_vccnz .LBB0_211
	s_barrier
	s_branch .LBB0_211

.LBB0_1563:
	v_mbcnt_lo_u32_b32 v240, -1, 0
	v_mbcnt_hi_u32_b32 v240, -1, v240
	s_lshl_b32 s16, s57, 7
	v_ashrrev_i32_e32 v242, 1, v240
	s_or_b32 s16, s16, s44
	v_and_b32_e32 v242, -8, v242
	v_add_u32_e32 v242, s16, v242
	v_ashrrev_i32_e32 v243, 31, v242
	v_lshlrev_b64 v[244:245], 2, v[242:243]
	v_lshl_add_u64 v[246:247], s[54:55], 0, v[244:245]
	v_lshl_add_u64 v[244:245], s[12:13], 0, v[244:245]
	s_lshl_b32 s16, s56, 8
	global_load_dwordx4 v[216:219], v[246:247], off
	global_load_dwordx4 v[220:223], v[246:247], off offset:16
	global_load_dwordx4 v[224:227], v[244:245], off
	global_load_dwordx4 v[228:231], v[244:245], off offset:16
	s_add_i32 s16, s16, s43
	v_and_or_b32 v242, v240, 15, s16
	v_ashrrev_i32_e32 v243, 31, v242
	v_lshl_add_u64 v[246:247], v[242:243], 2, s[4:5]
	global_load_dword v232, v[246:247], off
	global_load_dword v233, v[246:247], off offset:64
	global_load_dword v234, v[246:247], off offset:128
	global_load_dword v235, v[246:247], off offset:192
	global_load_dword v236, v[246:247], off offset:512
	global_load_dword v237, v[246:247], off offset:576
	global_load_dword v238, v[246:247], off offset:640
	global_load_dword v239, v[246:247], off offset:704
	s_waitcnt vmcnt(15)
	v_mov_b32_e32 v123, 0
	s_lshl_b32 s16, s53, 20
	s_lshl_b32 s17, s52, 20
	s_andn2_b64 vcc, exec, s[8:9]
	v_mov_b32_e32 v122, v123
	v_mov_b32_e32 v121, v123
	v_mov_b32_e32 v120, v123
	v_mov_b32_e32 v115, v123
	v_mov_b32_e32 v114, v123
	v_mov_b32_e32 v113, v123
	v_mov_b32_e32 v112, v123
	v_mov_b32_e32 v107, v123
	v_mov_b32_e32 v106, v123
	v_mov_b32_e32 v105, v123
	v_mov_b32_e32 v104, v123
	v_mov_b32_e32 v99, v123
	v_mov_b32_e32 v98, v123
	v_mov_b32_e32 v97, v123
	v_mov_b32_e32 v96, v123
	v_mov_b32_e32 v91, v123
	v_mov_b32_e32 v90, v123
	v_mov_b32_e32 v89, v123
	v_mov_b32_e32 v88, v123
	v_mov_b32_e32 v83, v123
	v_mov_b32_e32 v82, v123
	v_mov_b32_e32 v81, v123
	v_mov_b32_e32 v80, v123
	v_mov_b32_e32 v75, v123
	v_mov_b32_e32 v74, v123
	v_mov_b32_e32 v73, v123
	v_mov_b32_e32 v72, v123
	v_mov_b32_e32 v67, v123
	v_mov_b32_e32 v66, v123
	v_mov_b32_e32 v65, v123
	v_mov_b32_e32 v64, v123
	s_waitcnt vmcnt(14)
	v_mov_b32_e32 v127, v123
	v_mov_b32_e32 v126, v123
	v_mov_b32_e32 v125, v123
	v_mov_b32_e32 v124, v123
	v_mov_b32_e32 v119, v123
	v_mov_b32_e32 v118, v123
	v_mov_b32_e32 v117, v123
	v_mov_b32_e32 v116, v123
	v_mov_b32_e32 v111, v123
	v_mov_b32_e32 v110, v123
	v_mov_b32_e32 v109, v123
	v_mov_b32_e32 v108, v123
	v_mov_b32_e32 v103, v123
	v_mov_b32_e32 v102, v123
	v_mov_b32_e32 v101, v123
	v_mov_b32_e32 v100, v123
	v_mov_b32_e32 v95, v123
	v_mov_b32_e32 v94, v123
	v_mov_b32_e32 v93, v123
	v_mov_b32_e32 v92, v123
	v_mov_b32_e32 v87, v123
	v_mov_b32_e32 v86, v123
	v_mov_b32_e32 v85, v123
	v_mov_b32_e32 v84, v123
	v_mov_b32_e32 v79, v123
	v_mov_b32_e32 v78, v123
	v_mov_b32_e32 v77, v123
	v_mov_b32_e32 v76, v123
	v_mov_b32_e32 v71, v123
	v_mov_b32_e32 v70, v123
	v_mov_b32_e32 v69, v123
	v_mov_b32_e32 v68, v123
	v_mov_b32_e32 v59, v123
	v_mov_b32_e32 v58, v123
	v_mov_b32_e32 v57, v123
	v_mov_b32_e32 v56, v123
	v_mov_b32_e32 v51, v123
	v_mov_b32_e32 v50, v123
	v_mov_b32_e32 v49, v123
	v_mov_b32_e32 v48, v123
	v_mov_b32_e32 v43, v123
	v_mov_b32_e32 v42, v123
	v_mov_b32_e32 v41, v123
	v_mov_b32_e32 v40, v123
	v_mov_b32_e32 v35, v123
	v_mov_b32_e32 v34, v123
	v_mov_b32_e32 v33, v123
	v_mov_b32_e32 v32, v123
	v_mov_b32_e32 v27, v123
	v_mov_b32_e32 v26, v123
	v_mov_b32_e32 v25, v123
	v_mov_b32_e32 v24, v123
	v_mov_b32_e32 v19, v123
	v_mov_b32_e32 v18, v123
	v_mov_b32_e32 v17, v123
	v_mov_b32_e32 v16, v123
	v_mov_b32_e32 v11, v123
	v_mov_b32_e32 v10, v123
	v_mov_b32_e32 v9, v123
	v_mov_b32_e32 v8, v123
	v_mov_b32_e32 v3, v123
	v_mov_b32_e32 v2, v123
	v_mov_b32_e32 v1, v123
	v_mov_b32_e32 v0, v123
	v_mov_b32_e32 v63, v123
	v_mov_b32_e32 v62, v123
	v_mov_b32_e32 v61, v123
	v_mov_b32_e32 v60, v123
	v_mov_b32_e32 v55, v123
	v_mov_b32_e32 v54, v123
	v_mov_b32_e32 v53, v123
	v_mov_b32_e32 v52, v123
	v_mov_b32_e32 v47, v123
	v_mov_b32_e32 v46, v123
	v_mov_b32_e32 v45, v123
	v_mov_b32_e32 v44, v123
	v_mov_b32_e32 v39, v123
	v_mov_b32_e32 v38, v123
	v_mov_b32_e32 v37, v123
	v_mov_b32_e32 v36, v123
	v_mov_b32_e32 v31, v123
	v_mov_b32_e32 v30, v123
	v_mov_b32_e32 v29, v123
	v_mov_b32_e32 v28, v123
	v_mov_b32_e32 v23, v123
	v_mov_b32_e32 v22, v123
	v_mov_b32_e32 v21, v123
	v_mov_b32_e32 v20, v123
	v_mov_b32_e32 v15, v123
	v_mov_b32_e32 v14, v123
	v_mov_b32_e32 v13, v123
	v_mov_b32_e32 v12, v123
	v_mov_b32_e32 v7, v123
	v_mov_b32_e32 v6, v123
	v_mov_b32_e32 v5, v123
	v_mov_b32_e32 v4, v123
	s_cbranch_vccnz .LBB0_1566
	s_and_b64 s[22:23], s[0:1], exec
	s_cselect_b32 s58, s16, s60
	s_cselect_b32 s59, s17, s61
	s_add_i32 s60, s60, 0x80080
	s_addk_i32 s61, 0x100
	s_mov_b32 s62, 0
	v_mov_b32_e32 v4, 0
	v_mov_b32_e32 v5, 0
	v_mov_b32_e32 v6, 0
	v_mov_b32_e32 v7, 0
	v_mov_b32_e32 v12, 0
	v_mov_b32_e32 v13, 0
	v_mov_b32_e32 v14, 0
	v_mov_b32_e32 v15, 0
	v_mov_b32_e32 v20, 0
	v_mov_b32_e32 v21, 0
	v_mov_b32_e32 v22, 0
	v_mov_b32_e32 v23, 0
	v_mov_b32_e32 v28, 0
	v_mov_b32_e32 v29, 0
	v_mov_b32_e32 v30, 0
	v_mov_b32_e32 v31, 0
	v_mov_b32_e32 v36, 0
	v_mov_b32_e32 v37, 0
	v_mov_b32_e32 v38, 0
	v_mov_b32_e32 v39, 0
	v_mov_b32_e32 v44, 0
	v_mov_b32_e32 v45, 0
	v_mov_b32_e32 v46, 0
	v_mov_b32_e32 v47, 0
	v_mov_b32_e32 v52, 0
	v_mov_b32_e32 v53, 0
	v_mov_b32_e32 v54, 0
	v_mov_b32_e32 v55, 0
	v_mov_b32_e32 v60, 0
	v_mov_b32_e32 v61, 0
	v_mov_b32_e32 v62, 0
	v_mov_b32_e32 v63, 0
	v_mov_b32_e32 v0, 0
	v_mov_b32_e32 v1, 0
	v_mov_b32_e32 v2, 0
	v_mov_b32_e32 v3, 0
	v_mov_b32_e32 v8, 0
	v_mov_b32_e32 v9, 0
	v_mov_b32_e32 v10, 0
	v_mov_b32_e32 v11, 0
	v_mov_b32_e32 v16, 0
	v_mov_b32_e32 v17, 0
	v_mov_b32_e32 v18, 0
	v_mov_b32_e32 v19, 0
	v_mov_b32_e32 v24, 0
	v_mov_b32_e32 v25, 0
	v_mov_b32_e32 v26, 0
	v_mov_b32_e32 v27, 0
	v_mov_b32_e32 v32, 0
	v_mov_b32_e32 v33, 0
	v_mov_b32_e32 v34, 0
	v_mov_b32_e32 v35, 0
	v_mov_b32_e32 v40, 0
	v_mov_b32_e32 v41, 0
	v_mov_b32_e32 v42, 0
	v_mov_b32_e32 v43, 0
	v_mov_b32_e32 v48, 0
	v_mov_b32_e32 v49, 0
	v_mov_b32_e32 v50, 0
	v_mov_b32_e32 v51, 0
	v_mov_b32_e32 v56, 0
	v_mov_b32_e32 v57, 0
	v_mov_b32_e32 v58, 0
	v_mov_b32_e32 v59, 0
	v_mov_b32_e32 v68, 0
	v_mov_b32_e32 v69, 0
	v_mov_b32_e32 v70, 0
	v_mov_b32_e32 v71, 0
	v_mov_b32_e32 v76, 0
	v_mov_b32_e32 v77, 0
	v_mov_b32_e32 v78, 0
	v_mov_b32_e32 v79, 0
	v_mov_b32_e32 v84, 0
	v_mov_b32_e32 v85, 0
	v_mov_b32_e32 v86, 0
	v_mov_b32_e32 v87, 0
	v_mov_b32_e32 v92, 0
	v_mov_b32_e32 v93, 0
	v_mov_b32_e32 v94, 0
	v_mov_b32_e32 v95, 0
	v_mov_b32_e32 v100, 0
	v_mov_b32_e32 v101, 0
	v_mov_b32_e32 v102, 0
	v_mov_b32_e32 v103, 0
	v_mov_b32_e32 v108, 0
	v_mov_b32_e32 v109, 0
	v_mov_b32_e32 v110, 0
	v_mov_b32_e32 v111, 0
	v_mov_b32_e32 v116, 0
	v_mov_b32_e32 v117, 0
	v_mov_b32_e32 v118, 0
	v_mov_b32_e32 v119, 0
	v_mov_b32_e32 v124, 0
	v_mov_b32_e32 v125, 0
	v_mov_b32_e32 v126, 0
	v_mov_b32_e32 v127, 0
	v_mov_b32_e32 v64, 0
	v_mov_b32_e32 v65, 0
	v_mov_b32_e32 v66, 0
	v_mov_b32_e32 v67, 0
	v_mov_b32_e32 v72, 0
	v_mov_b32_e32 v73, 0
	v_mov_b32_e32 v74, 0
	v_mov_b32_e32 v75, 0
	v_mov_b32_e32 v80, 0
	v_mov_b32_e32 v81, 0
	v_mov_b32_e32 v82, 0
	v_mov_b32_e32 v83, 0
	v_mov_b32_e32 v88, 0
	v_mov_b32_e32 v89, 0
	v_mov_b32_e32 v90, 0
	v_mov_b32_e32 v91, 0
	v_mov_b32_e32 v96, 0
	v_mov_b32_e32 v97, 0
	v_mov_b32_e32 v98, 0
	v_mov_b32_e32 v99, 0
	v_mov_b32_e32 v104, 0
	v_mov_b32_e32 v105, 0
	v_mov_b32_e32 v106, 0
	v_mov_b32_e32 v107, 0
	v_mov_b32_e32 v112, 0
	v_mov_b32_e32 v113, 0
	v_mov_b32_e32 v114, 0
	v_mov_b32_e32 v115, 0
	v_mov_b32_e32 v120, 0
	v_mov_b32_e32 v121, 0
	v_mov_b32_e32 v122, 0
	v_mov_b32_e32 v123, 0

.LBB0_1568:
	v_mbcnt_lo_u32_b32 v140, -1, 0
	v_mbcnt_hi_u32_b32 v140, -1, v140
	s_lshl_b32 s22, s57, 7
	v_ashrrev_i32_e32 v132, 1, v140
	s_or_b32 s22, s22, s44
	v_and_b32_e32 v132, -8, v132
	v_add_u32_e32 v132, s22, v132
	v_ashrrev_i32_e32 v133, 31, v132
	v_lshlrev_b64 v[134:135], 2, v[132:133]
	s_lshl_b32 s22, s56, 8
	v_lshl_add_u64 v[158:159], s[54:55], 0, v[134:135]
	v_lshl_add_u64 v[134:135], s[12:13], 0, v[134:135]
	s_add_i32 s22, s22, s43
	v_mov_b32_e32 v136, v216
	v_mov_b32_e32 v137, v217
	v_mov_b32_e32 v138, v218
	v_mov_b32_e32 v139, v219
	v_mov_b32_e32 v154, v224
	v_mov_b32_e32 v155, v225
	v_mov_b32_e32 v156, v226
	v_mov_b32_e32 v157, v227
	s_nop 0
	v_mov_b32_e32 v158, v220
	v_mov_b32_e32 v159, v221
	v_mov_b32_e32 v160, v222
	v_mov_b32_e32 v161, v223
	s_nop 0
	v_mov_b32_e32 v162, v228
	v_mov_b32_e32 v163, v229
	v_mov_b32_e32 v164, v230
	v_mov_b32_e32 v165, v231
	v_and_or_b32 v134, v140, 15, s22
	v_ashrrev_i32_e32 v135, 31, v134
	v_lshl_add_u64 v[166:167], v[134:135], 2, s[4:5]
	v_mov_b32_e32 v168, v232
	v_cvt_f32_i32_e32 v174, v122
	v_cvt_f32_i32_e32 v122, v112
	v_mov_b32_e32 v184, v233
	v_mov_b32_e32 v148, v234
	v_mov_b32_e32 v146, v235
	v_mov_b32_e32 v144, v236
	v_mov_b32_e32 v142, v237
	v_mov_b32_e32 v140, v238
	v_mov_b32_e32 v112, v239
	v_cvt_f32_i32_e32 v171, v124
	v_cvt_f32_i32_e32 v170, v120
	v_cvt_f32_i32_e32 v173, v125
	v_cvt_f32_i32_e32 v172, v121
	v_cvt_f32_i32_e32 v175, v126
	v_cvt_f32_i32_e32 v176, v123
	v_cvt_f32_i32_e32 v123, v116
	v_cvt_f32_i32_e32 v179, v117
	v_cvt_f32_i32_e32 v178, v113
	v_cvt_f32_i32_e32 v180, v114
	v_cvt_f32_i32_e32 v182, v115
	v_cvt_f32_i32_e32 v181, v118
	v_cvt_f32_i32_e32 v183, v119
	v_cvt_f32_i32_e32 v177, v127
	v_add_u32_e32 v113, 0x80, v134
	v_mov_b32_e32 v115, v154
	v_mov_b32_e32 v114, v136
	v_mov_b32_e32 v154, v137
	v_mov_b32_e32 v116, v138
	v_mov_b32_e32 v117, v156
	v_mov_b32_e32 v156, v139
	v_mov_b32_e32 v118, v158
	v_mov_b32_e32 v119, v162
	v_mov_b32_e32 v162, v159
	v_pk_mul_f32 v[138:139], v[114:115], s[14:15]
	v_pk_mul_f32 v[136:137], v[154:155], s[14:15]
	v_mov_b32_e32 v158, v160
	v_mov_b32_e32 v159, v164
	v_mov_b32_e32 v164, v161
	v_pk_mul_f32 v[126:127], v[116:117], s[14:15]
	v_pk_mul_f32 v[124:125], v[156:157], s[14:15]
	v_pk_mul_f32 v[120:121], v[118:119], s[14:15]
	v_pk_mul_f32 v[118:119], v[162:163], s[14:15]
	v_pk_mul_f32 v[154:155], v[138:139], v[168:169] op_sel_hi:[1,0]
	v_pk_mul_f32 v[156:157], v[136:137], v[168:169] op_sel_hi:[1,0]
	v_pk_mul_f32 v[116:117], v[158:159], s[14:15]
	v_pk_mul_f32 v[114:115], v[164:165], s[14:15]
	v_pk_mul_f32 v[158:159], v[126:127], v[168:169] op_sel_hi:[1,0]
	v_pk_mul_f32 v[162:163], v[120:121], v[168:169] op_sel_hi:[1,0]
	v_pk_mul_f32 v[164:165], v[118:119], v[168:169] op_sel_hi:[1,0]
	v_pk_mul_f32 v[154:155], v[154:155], v[170:171]
	v_pk_mul_f32 v[156:157], v[156:157], v[172:173]
	v_pk_mul_f32 v[160:161], v[124:125], v[168:169] op_sel_hi:[1,0]
	v_pk_mul_f32 v[166:167], v[116:117], v[168:169] op_sel_hi:[1,0]
	v_pk_mul_f32 v[168:169], v[114:115], v[168:169] op_sel_hi:[1,0]
	v_pk_mul_f32 v[158:159], v[158:159], v[174:175]
	v_pk_mul_f32 v[122:123], v[162:163], v[122:123]
	v_pk_mul_f32 v[162:163], v[164:165], v[178:179]
	v_mul_f32_e32 v135, 0xbfb8aa3b, v154
	v_mul_f32_e32 v153, 0xbfb8aa3b, v156
	v_pk_mul_f32 v[164:165], v[166:167], v[180:181]
	v_pk_mul_f32 v[166:167], v[168:169], v[182:183]
	v_mul_f32_e32 v168, 0xbfb8aa3b, v158
	v_mul_f32_e32 v170, 0xbfb8aa3b, v122
	v_mul_f32_e32 v171, 0xbfb8aa3b, v162
	v_exp_f32_e32 v135, v135
	v_exp_f32_e32 v153, v153
	v_exp_f32_e32 v168, v168
	v_exp_f32_e32 v170, v170
	v_exp_f32_e32 v171, v171
	v_pk_mul_f32 v[160:161], v[160:161], v[176:177]
	v_mul_f32_e32 v172, 0xbfb8aa3b, v164
	v_mul_f32_e32 v169, 0xbfb8aa3b, v160
	v_mul_f32_e32 v173, 0xbfb8aa3b, v166
	v_add_f32_e32 v135, 1.0, v135
	v_add_f32_e32 v153, 1.0, v153
	v_exp_f32_e32 v169, v169
	v_exp_f32_e32 v172, v172
	v_exp_f32_e32 v173, v173
	v_mul_f32_e32 v154, v154, v155
	v_mul_f32_e32 v155, v156, v157
	v_mul_f32_e32 v157, v160, v161
	v_mul_f32_e32 v122, v122, v123
	v_mul_f32_e32 v123, v162, v163
	v_rcp_f32_e32 v135, v135
	v_rcp_f32_e32 v153, v153
	v_add_f32_e32 v160, 1.0, v168
	v_add_f32_e32 v162, 1.0, v170
	v_add_f32_e32 v163, 1.0, v171
	v_rcp_f32_e32 v160, v160
	v_rcp_f32_e32 v162, v162
	v_rcp_f32_e32 v163, v163
	v_mul_f32_e32 v156, v158, v159
	v_mul_f32_e32 v158, v164, v165
	v_add_f32_e32 v161, 1.0, v169
	v_add_f32_e32 v164, 1.0, v172
	v_add_f32_e32 v165, 1.0, v173
	v_mul_f32_e32 v135, v154, v135
	v_mul_f32_e32 v153, v155, v153
	v_rcp_f32_e32 v161, v161
	v_rcp_f32_e32 v164, v164
	v_rcp_f32_e32 v165, v165
	v_mul_f32_e32 v155, v156, v160
	v_mul_f32_e32 v122, v122, v162
	v_mul_f32_e32 v123, v123, v163
	v_med3_f32 v135, v135, s50, v152
	v_med3_f32 v153, v153, s50, v152
	v_mov_b32_e32 v154, 0
	v_cvt_pk_fp8_f32 v154, v135, v153
	v_med3_f32 v135, v155, s50, v152
	v_med3_f32 v122, v122, s50, v152
	v_med3_f32 v123, v123, s50, v152
	v_mov_b32_e32 v155, 0
	v_cvt_pk_fp8_f32 v155, v122, v123
	v_mul_f32_e32 v159, v166, v167
	v_mul_f32_e32 v156, v157, v161
	v_mul_f32_e32 v157, v158, v164
	v_mul_f32_e32 v158, v159, v165
	v_med3_f32 v153, v156, s50, v152
	v_med3_f32 v122, v157, s50, v152
	v_med3_f32 v123, v158, s50, v152
	v_cvt_pk_fp8_f32 v154, v135, v153 op_sel:[0,0,1]
	v_cvt_pk_fp8_f32 v155, v122, v123 op_sel:[0,0,1]
	v_mov_b64_e32 v[122:123], s[76:77]
	v_mad_i64_i32 v[156:157], s[22:23], v134, s51, v[122:123]
	v_lshl_add_u64 v[156:157], v[156:157], 0, v[132:133]
	global_store_dwordx2 v[156:157], v[154:155], off
	v_cvt_f32_i32_e32 v155, v108
	v_cvt_f32_i32_e32 v154, v104
	v_cvt_f32_i32_e32 v109, v109
	v_cvt_f32_i32_e32 v108, v105
	v_pk_mul_f32 v[104:105], v[138:139], v[184:185] op_sel_hi:[1,0]
	v_cvt_f32_i32_e32 v111, v111
	v_pk_mul_f32 v[104:105], v[104:105], v[154:155]
	v_pk_mul_f32 v[154:155], v[136:137], v[184:185] op_sel_hi:[1,0]
	v_cvt_f32_i32_e32 v101, v101
	v_pk_mul_f32 v[108:109], v[154:155], v[108:109]
	v_cvt_f32_i32_e32 v155, v110
	v_cvt_f32_i32_e32 v154, v106
	v_cvt_f32_i32_e32 v110, v107
	v_pk_mul_f32 v[106:107], v[126:127], v[184:185] op_sel_hi:[1,0]
	v_cvt_f32_i32_e32 v103, v103
	v_pk_mul_f32 v[106:107], v[106:107], v[154:155]
	v_pk_mul_f32 v[154:155], v[124:125], v[184:185] op_sel_hi:[1,0]
	v_mul_f32_e32 v153, 0xbfb8aa3b, v104
	v_pk_mul_f32 v[110:111], v[154:155], v[110:111]
	v_cvt_f32_i32_e32 v155, v100
	v_cvt_f32_i32_e32 v154, v96
	v_cvt_f32_i32_e32 v100, v97
	v_pk_mul_f32 v[96:97], v[120:121], v[184:185] op_sel_hi:[1,0]
	v_exp_f32_e32 v153, v153
	v_pk_mul_f32 v[96:97], v[96:97], v[154:155]
	v_pk_mul_f32 v[154:155], v[118:119], v[184:185] op_sel_hi:[1,0]
	v_mul_f32_e32 v156, 0xbfb8aa3b, v110
	v_pk_mul_f32 v[100:101], v[154:155], v[100:101]
	v_cvt_f32_i32_e32 v155, v102
	v_cvt_f32_i32_e32 v154, v98
	v_cvt_f32_i32_e32 v102, v99
	v_pk_mul_f32 v[98:99], v[116:117], v[184:185] op_sel_hi:[1,0]
	v_mul_f32_e32 v157, 0xbfb8aa3b, v96
	v_pk_mul_f32 v[98:99], v[98:99], v[154:155]
	v_pk_mul_f32 v[154:155], v[114:115], v[184:185] op_sel_hi:[1,0]
	v_mul_f32_e32 v158, 0xbfb8aa3b, v100
	v_pk_mul_f32 v[102:103], v[154:155], v[102:103]
	v_mul_f32_e32 v154, 0xbfb8aa3b, v108
	v_exp_f32_e32 v154, v154
	v_mul_f32_e32 v155, 0xbfb8aa3b, v106
	v_exp_f32_e32 v155, v155
	v_exp_f32_e32 v156, v156
	v_exp_f32_e32 v157, v157
	v_exp_f32_e32 v158, v158
	v_mul_f32_e32 v159, 0xbfb8aa3b, v98
	v_mul_f32_e32 v160, 0xbfb8aa3b, v102
	v_mul_f32_e32 v96, v96, v97
	v_mul_f32_e32 v97, v100, v101
	v_add_f32_e32 v100, 1.0, v153
	v_add_f32_e32 v101, 1.0, v154
	v_exp_f32_e32 v159, v159
	v_exp_f32_e32 v160, v160
	v_mul_f32_e32 v104, v104, v105
	v_mul_f32_e32 v105, v108, v109
	v_mul_f32_e32 v98, v98, v99
	v_mul_f32_e32 v99, v102, v103
	v_rcp_f32_e32 v100, v100
	v_rcp_f32_e32 v101, v101
	v_add_f32_e32 v102, 1.0, v155
	v_add_f32_e32 v103, 1.0, v156
	v_add_f32_e32 v108, 1.0, v157
	v_add_f32_e32 v109, 1.0, v158
	v_rcp_f32_e32 v102, v102
	v_rcp_f32_e32 v103, v103
	v_rcp_f32_e32 v108, v108
	v_rcp_f32_e32 v109, v109
	v_mul_f32_e32 v106, v106, v107
	v_mul_f32_e32 v107, v110, v111
	v_add_f32_e32 v110, 1.0, v159
	v_add_f32_e32 v111, 1.0, v160
	v_mul_f32_e32 v100, v104, v100
	v_mul_f32_e32 v101, v105, v101
	v_rcp_f32_e32 v110, v110
	v_rcp_f32_e32 v111, v111
	v_mul_f32_e32 v102, v106, v102
	v_mul_f32_e32 v103, v107, v103
	v_mul_f32_e32 v104, v96, v108
	v_mul_f32_e32 v97, v97, v109
	v_med3_f32 v100, v100, s50, v152
	v_med3_f32 v101, v101, s50, v152
	v_mov_b32_e32 v96, 0
	v_cvt_pk_fp8_f32 v96, v100, v101
	v_med3_f32 v100, v102, s50, v152
	v_med3_f32 v101, v103, s50, v152
	v_med3_f32 v102, v104, s50, v152
	v_med3_f32 v103, v97, s50, v152
	v_mov_b32_e32 v97, 0
	v_cvt_pk_fp8_f32 v97, v102, v103
	v_mul_f32_e32 v98, v98, v110
	v_mul_f32_e32 v99, v99, v111
	v_med3_f32 v98, v98, s50, v152
	v_med3_f32 v99, v99, s50, v152
	v_cvt_pk_fp8_f32 v96, v100, v101 op_sel:[0,0,1]
	v_cvt_pk_fp8_f32 v97, v98, v99 op_sel:[0,0,1]
	v_or_b32_e32 v135, 16, v134
	v_mad_i64_i32 v[98:99], s[22:23], v135, s51, v[122:123]
	v_lshl_add_u64 v[98:99], v[98:99], 0, v[132:133]
	global_store_dwordx2 v[98:99], v[96:97], off
	v_cvt_f32_i32_e32 v97, v92
	v_cvt_f32_i32_e32 v96, v88
	v_cvt_f32_i32_e32 v93, v93
	v_cvt_f32_i32_e32 v92, v89
	v_pk_mul_f32 v[88:89], v[138:139], v[148:149] op_sel_hi:[1,0]
	v_cvt_f32_i32_e32 v95, v95
	v_pk_mul_f32 v[88:89], v[88:89], v[96:97]
	v_pk_mul_f32 v[96:97], v[136:137], v[148:149] op_sel_hi:[1,0]
	v_cvt_f32_i32_e32 v85, v85
	v_pk_mul_f32 v[92:93], v[96:97], v[92:93]
	v_cvt_f32_i32_e32 v97, v94
	v_cvt_f32_i32_e32 v96, v90
	v_cvt_f32_i32_e32 v94, v91
	v_pk_mul_f32 v[90:91], v[126:127], v[148:149] op_sel_hi:[1,0]
	v_cvt_f32_i32_e32 v87, v87
	v_pk_mul_f32 v[90:91], v[90:91], v[96:97]
	v_pk_mul_f32 v[96:97], v[124:125], v[148:149] op_sel_hi:[1,0]
	v_mul_f32_e32 v99, 0xbfb8aa3b, v90
	v_pk_mul_f32 v[94:95], v[96:97], v[94:95]
	v_cvt_f32_i32_e32 v97, v84
	v_cvt_f32_i32_e32 v96, v80
	v_cvt_f32_i32_e32 v84, v81
	v_pk_mul_f32 v[80:81], v[120:121], v[148:149] op_sel_hi:[1,0]
	v_mul_f32_e32 v100, 0xbfb8aa3b, v94
	v_pk_mul_f32 v[80:81], v[80:81], v[96:97]
	v_pk_mul_f32 v[96:97], v[118:119], v[148:149] op_sel_hi:[1,0]
	v_mul_f32_e32 v101, 0xbfb8aa3b, v80
	v_pk_mul_f32 v[84:85], v[96:97], v[84:85]
	v_cvt_f32_i32_e32 v97, v86
	v_cvt_f32_i32_e32 v96, v82
	v_cvt_f32_i32_e32 v86, v83
	v_pk_mul_f32 v[82:83], v[116:117], v[148:149] op_sel_hi:[1,0]
	v_mul_f32_e32 v102, 0xbfb8aa3b, v84
	v_pk_mul_f32 v[82:83], v[82:83], v[96:97]
	v_pk_mul_f32 v[96:97], v[114:115], v[148:149] op_sel_hi:[1,0]
	v_exp_f32_e32 v99, v99
	v_pk_mul_f32 v[86:87], v[96:97], v[86:87]
	v_mul_f32_e32 v96, 0xbfb8aa3b, v88
	v_mul_f32_e32 v97, 0xbfb8aa3b, v92
	v_exp_f32_e32 v96, v96
	v_exp_f32_e32 v97, v97
	v_exp_f32_e32 v100, v100
	v_exp_f32_e32 v101, v101
	v_exp_f32_e32 v102, v102
	v_mul_f32_e32 v103, 0xbfb8aa3b, v82
	v_mul_f32_e32 v104, 0xbfb8aa3b, v86
	v_mul_f32_e32 v80, v80, v81
	v_mul_f32_e32 v81, v84, v85
	v_add_f32_e32 v84, 1.0, v96
	v_add_f32_e32 v85, 1.0, v97
	v_exp_f32_e32 v103, v103
	v_exp_f32_e32 v104, v104
	v_mul_f32_e32 v88, v88, v89
	v_mul_f32_e32 v89, v92, v93
	v_mul_f32_e32 v82, v82, v83
	v_mul_f32_e32 v83, v86, v87
	v_rcp_f32_e32 v84, v84
	v_rcp_f32_e32 v85, v85
	v_add_f32_e32 v86, 1.0, v99
	v_add_f32_e32 v87, 1.0, v100
	v_add_f32_e32 v92, 1.0, v101
	v_add_f32_e32 v93, 1.0, v102
	v_rcp_f32_e32 v86, v86
	v_rcp_f32_e32 v87, v87
	v_rcp_f32_e32 v92, v92
	v_rcp_f32_e32 v93, v93
	v_mul_f32_e32 v90, v90, v91
	v_mul_f32_e32 v91, v94, v95
	v_add_f32_e32 v94, 1.0, v103
	v_add_f32_e32 v95, 1.0, v104
	v_mul_f32_e32 v84, v88, v84
	v_mul_f32_e32 v85, v89, v85
	v_rcp_f32_e32 v94, v94
	v_rcp_f32_e32 v95, v95
	v_mul_f32_e32 v86, v90, v86
	v_mul_f32_e32 v87, v91, v87
	v_mul_f32_e32 v88, v80, v92
	v_mul_f32_e32 v81, v81, v93
	v_med3_f32 v84, v84, s50, v152
	v_med3_f32 v85, v85, s50, v152
	v_mov_b32_e32 v80, 0
	v_cvt_pk_fp8_f32 v80, v84, v85
	v_med3_f32 v84, v86, s50, v152
	v_med3_f32 v85, v87, s50, v152
	v_med3_f32 v86, v88, s50, v152
	v_med3_f32 v87, v81, s50, v152
	v_mov_b32_e32 v81, 0
	v_cvt_pk_fp8_f32 v81, v86, v87
	v_mul_f32_e32 v82, v82, v94
	v_mul_f32_e32 v83, v83, v95
	v_med3_f32 v82, v82, s50, v152
	v_med3_f32 v83, v83, s50, v152
	v_cvt_pk_fp8_f32 v80, v84, v85 op_sel:[0,0,1]
	v_cvt_pk_fp8_f32 v81, v82, v83 op_sel:[0,0,1]
	v_or_b32_e32 v98, 32, v134
	v_mad_i64_i32 v[82:83], s[22:23], v98, s51, v[122:123]
	v_lshl_add_u64 v[82:83], v[82:83], 0, v[132:133]
	global_store_dwordx2 v[82:83], v[80:81], off
	v_cvt_f32_i32_e32 v81, v76
	v_cvt_f32_i32_e32 v80, v72
	v_cvt_f32_i32_e32 v77, v77
	v_cvt_f32_i32_e32 v76, v73
	v_pk_mul_f32 v[72:73], v[138:139], v[146:147] op_sel_hi:[1,0]
	v_cvt_f32_i32_e32 v79, v79
	v_pk_mul_f32 v[72:73], v[72:73], v[80:81]
	v_pk_mul_f32 v[80:81], v[136:137], v[146:147] op_sel_hi:[1,0]
	v_cvt_f32_i32_e32 v69, v69
	v_pk_mul_f32 v[76:77], v[80:81], v[76:77]
	v_cvt_f32_i32_e32 v81, v78
	v_cvt_f32_i32_e32 v80, v74
	v_cvt_f32_i32_e32 v78, v75
	v_pk_mul_f32 v[74:75], v[126:127], v[146:147] op_sel_hi:[1,0]
	v_cvt_f32_i32_e32 v71, v71
	v_pk_mul_f32 v[74:75], v[74:75], v[80:81]
	v_pk_mul_f32 v[80:81], v[124:125], v[146:147] op_sel_hi:[1,0]
	v_mul_f32_e32 v83, 0xbfb8aa3b, v74
	v_pk_mul_f32 v[78:79], v[80:81], v[78:79]
	v_cvt_f32_i32_e32 v81, v68
	v_cvt_f32_i32_e32 v80, v64
	v_cvt_f32_i32_e32 v68, v65
	v_pk_mul_f32 v[64:65], v[120:121], v[146:147] op_sel_hi:[1,0]
	v_mul_f32_e32 v84, 0xbfb8aa3b, v78
	v_pk_mul_f32 v[64:65], v[64:65], v[80:81]
	v_pk_mul_f32 v[80:81], v[118:119], v[146:147] op_sel_hi:[1,0]
	v_mul_f32_e32 v85, 0xbfb8aa3b, v64
	v_pk_mul_f32 v[68:69], v[80:81], v[68:69]
	v_cvt_f32_i32_e32 v81, v70
	v_cvt_f32_i32_e32 v80, v66
	v_cvt_f32_i32_e32 v70, v67
	v_pk_mul_f32 v[66:67], v[116:117], v[146:147] op_sel_hi:[1,0]
	v_mul_f32_e32 v86, 0xbfb8aa3b, v68
	v_pk_mul_f32 v[66:67], v[66:67], v[80:81]
	v_pk_mul_f32 v[80:81], v[114:115], v[146:147] op_sel_hi:[1,0]
	v_exp_f32_e32 v83, v83
	v_pk_mul_f32 v[70:71], v[80:81], v[70:71]
	v_mul_f32_e32 v80, 0xbfb8aa3b, v72
	v_mul_f32_e32 v81, 0xbfb8aa3b, v76
	v_exp_f32_e32 v80, v80
	v_exp_f32_e32 v81, v81
	v_exp_f32_e32 v84, v84
	v_exp_f32_e32 v85, v85
	v_exp_f32_e32 v86, v86
	v_mul_f32_e32 v87, 0xbfb8aa3b, v66
	v_mul_f32_e32 v88, 0xbfb8aa3b, v70
	v_mul_f32_e32 v64, v64, v65
	v_mul_f32_e32 v65, v68, v69
	v_add_f32_e32 v68, 1.0, v80
	v_add_f32_e32 v69, 1.0, v81
	v_exp_f32_e32 v87, v87
	v_exp_f32_e32 v88, v88
	v_mul_f32_e32 v72, v72, v73
	v_mul_f32_e32 v73, v76, v77
	v_mul_f32_e32 v66, v66, v67
	v_mul_f32_e32 v67, v70, v71
	v_rcp_f32_e32 v68, v68
	v_rcp_f32_e32 v69, v69
	v_add_f32_e32 v70, 1.0, v83
	v_add_f32_e32 v71, 1.0, v84
	v_add_f32_e32 v76, 1.0, v85
	v_add_f32_e32 v77, 1.0, v86
	v_rcp_f32_e32 v70, v70
	v_rcp_f32_e32 v71, v71
	v_rcp_f32_e32 v76, v76
	v_rcp_f32_e32 v77, v77
	v_mul_f32_e32 v74, v74, v75
	v_mul_f32_e32 v75, v78, v79
	v_add_f32_e32 v78, 1.0, v87
	v_add_f32_e32 v79, 1.0, v88
	v_mul_f32_e32 v68, v72, v68
	v_mul_f32_e32 v69, v73, v69
	v_rcp_f32_e32 v78, v78
	v_rcp_f32_e32 v79, v79
	v_mul_f32_e32 v70, v74, v70
	v_mul_f32_e32 v71, v75, v71
	v_mul_f32_e32 v72, v64, v76
	v_mul_f32_e32 v65, v65, v77
	v_med3_f32 v68, v68, s50, v152
	v_med3_f32 v69, v69, s50, v152
	v_mov_b32_e32 v64, 0
	v_cvt_pk_fp8_f32 v64, v68, v69
	v_med3_f32 v68, v70, s50, v152
	v_med3_f32 v69, v71, s50, v152
	v_med3_f32 v70, v72, s50, v152
	v_med3_f32 v71, v65, s50, v152
	v_mov_b32_e32 v65, 0
	v_cvt_pk_fp8_f32 v65, v70, v71
	v_mul_f32_e32 v66, v66, v78
	v_mul_f32_e32 v67, v67, v79
	v_med3_f32 v66, v66, s50, v152
	v_med3_f32 v67, v67, s50, v152
	v_cvt_pk_fp8_f32 v64, v68, v69 op_sel:[0,0,1]
	v_cvt_pk_fp8_f32 v65, v66, v67 op_sel:[0,0,1]
	v_or_b32_e32 v82, 48, v134
	v_mad_i64_i32 v[66:67], s[22:23], v82, s51, v[122:123]
	v_lshl_add_u64 v[66:67], v[66:67], 0, v[132:133]
	global_store_dwordx2 v[66:67], v[64:65], off
	v_cvt_f32_i32_e32 v65, v60
	v_cvt_f32_i32_e32 v64, v56
	v_cvt_f32_i32_e32 v61, v61
	v_cvt_f32_i32_e32 v60, v57
	v_pk_mul_f32 v[56:57], v[138:139], v[144:145] op_sel_hi:[1,0]
	v_cvt_f32_i32_e32 v63, v63
	v_pk_mul_f32 v[56:57], v[56:57], v[64:65]
	v_pk_mul_f32 v[64:65], v[136:137], v[144:145] op_sel_hi:[1,0]
	v_cvt_f32_i32_e32 v53, v53
	v_pk_mul_f32 v[60:61], v[64:65], v[60:61]
	v_cvt_f32_i32_e32 v65, v62
	v_cvt_f32_i32_e32 v64, v58
	v_cvt_f32_i32_e32 v62, v59
	v_pk_mul_f32 v[58:59], v[126:127], v[144:145] op_sel_hi:[1,0]
	v_cvt_f32_i32_e32 v55, v55
	v_pk_mul_f32 v[58:59], v[58:59], v[64:65]
	v_pk_mul_f32 v[64:65], v[124:125], v[144:145] op_sel_hi:[1,0]
	v_mul_f32_e32 v66, 0xbfb8aa3b, v58
	v_pk_mul_f32 v[62:63], v[64:65], v[62:63]
	v_cvt_f32_i32_e32 v65, v52
	v_cvt_f32_i32_e32 v64, v48
	v_cvt_f32_i32_e32 v52, v49
	v_pk_mul_f32 v[48:49], v[120:121], v[144:145] op_sel_hi:[1,0]
	v_mul_f32_e32 v67, 0xbfb8aa3b, v62
	v_pk_mul_f32 v[48:49], v[48:49], v[64:65]
	v_pk_mul_f32 v[64:65], v[118:119], v[144:145] op_sel_hi:[1,0]
	v_mul_f32_e32 v68, 0xbfb8aa3b, v48
	v_pk_mul_f32 v[52:53], v[64:65], v[52:53]
	v_cvt_f32_i32_e32 v65, v54
	v_cvt_f32_i32_e32 v64, v50
	v_cvt_f32_i32_e32 v54, v51
	v_pk_mul_f32 v[50:51], v[116:117], v[144:145] op_sel_hi:[1,0]
	v_mul_f32_e32 v69, 0xbfb8aa3b, v52
	v_pk_mul_f32 v[50:51], v[50:51], v[64:65]
	v_pk_mul_f32 v[64:65], v[114:115], v[144:145] op_sel_hi:[1,0]
	v_exp_f32_e32 v66, v66
	v_pk_mul_f32 v[54:55], v[64:65], v[54:55]
	v_mul_f32_e32 v64, 0xbfb8aa3b, v56
	v_mul_f32_e32 v65, 0xbfb8aa3b, v60
	v_exp_f32_e32 v64, v64
	v_exp_f32_e32 v65, v65
	v_exp_f32_e32 v67, v67
	v_exp_f32_e32 v68, v68
	v_exp_f32_e32 v69, v69
	v_mul_f32_e32 v70, 0xbfb8aa3b, v50
	v_mul_f32_e32 v71, 0xbfb8aa3b, v54
	v_mul_f32_e32 v48, v48, v49
	v_mul_f32_e32 v49, v52, v53
	v_add_f32_e32 v52, 1.0, v64
	v_add_f32_e32 v53, 1.0, v65
	v_exp_f32_e32 v70, v70
	v_exp_f32_e32 v71, v71
	v_mul_f32_e32 v56, v56, v57
	v_mul_f32_e32 v57, v60, v61
	v_mul_f32_e32 v50, v50, v51
	v_mul_f32_e32 v51, v54, v55
	v_rcp_f32_e32 v52, v52
	v_rcp_f32_e32 v53, v53
	v_add_f32_e32 v54, 1.0, v66
	v_add_f32_e32 v55, 1.0, v67
	v_add_f32_e32 v60, 1.0, v68
	v_add_f32_e32 v61, 1.0, v69
	v_rcp_f32_e32 v54, v54
	v_rcp_f32_e32 v55, v55
	v_rcp_f32_e32 v60, v60
	v_rcp_f32_e32 v61, v61
	v_mul_f32_e32 v58, v58, v59
	v_mul_f32_e32 v59, v62, v63
	v_add_f32_e32 v62, 1.0, v70
	v_add_f32_e32 v63, 1.0, v71
	v_mul_f32_e32 v52, v56, v52
	v_mul_f32_e32 v53, v57, v53
	v_rcp_f32_e32 v62, v62
	v_rcp_f32_e32 v63, v63
	v_mul_f32_e32 v54, v58, v54
	v_mul_f32_e32 v55, v59, v55
	v_mul_f32_e32 v56, v48, v60
	v_mul_f32_e32 v49, v49, v61
	v_med3_f32 v52, v52, s50, v152
	v_med3_f32 v53, v53, s50, v152
	v_mov_b32_e32 v48, 0
	v_cvt_pk_fp8_f32 v48, v52, v53
	v_med3_f32 v52, v54, s50, v152
	v_med3_f32 v53, v55, s50, v152
	v_med3_f32 v54, v56, s50, v152
	v_med3_f32 v55, v49, s50, v152
	v_mov_b32_e32 v49, 0
	v_cvt_pk_fp8_f32 v49, v54, v55
	v_mul_f32_e32 v50, v50, v62
	v_mul_f32_e32 v51, v51, v63
	v_med3_f32 v50, v50, s50, v152
	v_med3_f32 v51, v51, s50, v152
	v_cvt_pk_fp8_f32 v48, v52, v53 op_sel:[0,0,1]
	v_cvt_pk_fp8_f32 v49, v50, v51 op_sel:[0,0,1]
	v_mad_i64_i32 v[50:51], s[22:23], v113, s51, v[122:123]
	v_lshl_add_u64 v[50:51], v[50:51], 0, v[132:133]
	global_store_dwordx2 v[50:51], v[48:49], off
	v_cvt_f32_i32_e32 v49, v44
	v_cvt_f32_i32_e32 v48, v40
	v_cvt_f32_i32_e32 v45, v45
	v_cvt_f32_i32_e32 v44, v41
	v_pk_mul_f32 v[40:41], v[138:139], v[142:143] op_sel_hi:[1,0]
	v_cvt_f32_i32_e32 v47, v47
	v_pk_mul_f32 v[40:41], v[40:41], v[48:49]
	v_pk_mul_f32 v[48:49], v[136:137], v[142:143] op_sel_hi:[1,0]
	v_cvt_f32_i32_e32 v37, v37
	v_pk_mul_f32 v[44:45], v[48:49], v[44:45]
	v_cvt_f32_i32_e32 v49, v46
	v_cvt_f32_i32_e32 v48, v42
	v_cvt_f32_i32_e32 v46, v43
	v_pk_mul_f32 v[42:43], v[126:127], v[142:143] op_sel_hi:[1,0]
	v_cvt_f32_i32_e32 v39, v39
	v_pk_mul_f32 v[42:43], v[42:43], v[48:49]
	v_pk_mul_f32 v[48:49], v[124:125], v[142:143] op_sel_hi:[1,0]
	v_mul_f32_e32 v51, 0xbfb8aa3b, v42
	v_pk_mul_f32 v[46:47], v[48:49], v[46:47]
	v_cvt_f32_i32_e32 v49, v36
	v_cvt_f32_i32_e32 v48, v32
	v_cvt_f32_i32_e32 v36, v33
	v_pk_mul_f32 v[32:33], v[120:121], v[142:143] op_sel_hi:[1,0]
	v_mul_f32_e32 v52, 0xbfb8aa3b, v46
	v_pk_mul_f32 v[32:33], v[32:33], v[48:49]
	v_pk_mul_f32 v[48:49], v[118:119], v[142:143] op_sel_hi:[1,0]
	v_mul_f32_e32 v53, 0xbfb8aa3b, v32
	v_pk_mul_f32 v[36:37], v[48:49], v[36:37]
	v_cvt_f32_i32_e32 v49, v38
	v_cvt_f32_i32_e32 v48, v34
	v_cvt_f32_i32_e32 v38, v35
	v_pk_mul_f32 v[34:35], v[116:117], v[142:143] op_sel_hi:[1,0]
	v_mul_f32_e32 v54, 0xbfb8aa3b, v36
	v_pk_mul_f32 v[34:35], v[34:35], v[48:49]
	v_pk_mul_f32 v[48:49], v[114:115], v[142:143] op_sel_hi:[1,0]
	v_exp_f32_e32 v51, v51
	v_pk_mul_f32 v[38:39], v[48:49], v[38:39]
	v_mul_f32_e32 v48, 0xbfb8aa3b, v40
	v_mul_f32_e32 v49, 0xbfb8aa3b, v44
	v_exp_f32_e32 v48, v48
	v_exp_f32_e32 v49, v49
	v_exp_f32_e32 v52, v52
	v_exp_f32_e32 v53, v53
	v_exp_f32_e32 v54, v54
	v_mul_f32_e32 v55, 0xbfb8aa3b, v34
	v_mul_f32_e32 v56, 0xbfb8aa3b, v38
	v_mul_f32_e32 v32, v32, v33
	v_mul_f32_e32 v33, v36, v37
	v_add_f32_e32 v36, 1.0, v48
	v_add_f32_e32 v37, 1.0, v49
	v_exp_f32_e32 v55, v55
	v_exp_f32_e32 v56, v56
	v_mul_f32_e32 v40, v40, v41
	v_mul_f32_e32 v41, v44, v45
	v_mul_f32_e32 v34, v34, v35
	v_mul_f32_e32 v35, v38, v39
	v_rcp_f32_e32 v36, v36
	v_rcp_f32_e32 v37, v37
	v_add_f32_e32 v38, 1.0, v51
	v_add_f32_e32 v39, 1.0, v52
	v_add_f32_e32 v44, 1.0, v53
	v_add_f32_e32 v45, 1.0, v54
	v_rcp_f32_e32 v38, v38
	v_rcp_f32_e32 v39, v39
	v_rcp_f32_e32 v44, v44
	v_rcp_f32_e32 v45, v45
	v_mul_f32_e32 v42, v42, v43
	v_mul_f32_e32 v43, v46, v47
	v_add_f32_e32 v46, 1.0, v55
	v_add_f32_e32 v47, 1.0, v56
	v_mul_f32_e32 v36, v40, v36
	v_mul_f32_e32 v37, v41, v37
	v_rcp_f32_e32 v46, v46
	v_rcp_f32_e32 v47, v47
	v_mul_f32_e32 v38, v42, v38
	v_mul_f32_e32 v39, v43, v39
	v_mul_f32_e32 v40, v32, v44
	v_mul_f32_e32 v33, v33, v45
	v_med3_f32 v36, v36, s50, v152
	v_med3_f32 v37, v37, s50, v152
	v_mov_b32_e32 v32, 0
	v_cvt_pk_fp8_f32 v32, v36, v37
	v_med3_f32 v36, v38, s50, v152
	v_med3_f32 v37, v39, s50, v152
	v_med3_f32 v38, v40, s50, v152
	v_med3_f32 v39, v33, s50, v152
	v_mov_b32_e32 v33, 0
	v_cvt_pk_fp8_f32 v33, v38, v39
	v_mul_f32_e32 v34, v34, v46
	v_mul_f32_e32 v35, v35, v47
	v_med3_f32 v34, v34, s50, v152
	v_med3_f32 v35, v35, s50, v152
	v_cvt_pk_fp8_f32 v32, v36, v37 op_sel:[0,0,1]
	v_cvt_pk_fp8_f32 v33, v34, v35 op_sel:[0,0,1]
	v_add_u32_e32 v50, 0x90, v134
	v_mad_i64_i32 v[34:35], s[22:23], v50, s51, v[122:123]
	v_lshl_add_u64 v[34:35], v[34:35], 0, v[132:133]
	global_store_dwordx2 v[34:35], v[32:33], off
	v_cvt_f32_i32_e32 v33, v28
	v_cvt_f32_i32_e32 v32, v24
	v_cvt_f32_i32_e32 v29, v29
	v_cvt_f32_i32_e32 v28, v25
	v_pk_mul_f32 v[24:25], v[138:139], v[140:141] op_sel_hi:[1,0]
	v_cvt_f32_i32_e32 v31, v31
	v_pk_mul_f32 v[24:25], v[24:25], v[32:33]
	v_pk_mul_f32 v[32:33], v[136:137], v[140:141] op_sel_hi:[1,0]
	v_cvt_f32_i32_e32 v21, v21
	v_pk_mul_f32 v[28:29], v[32:33], v[28:29]
	v_cvt_f32_i32_e32 v33, v30
	v_cvt_f32_i32_e32 v32, v26
	v_cvt_f32_i32_e32 v30, v27
	v_pk_mul_f32 v[26:27], v[126:127], v[140:141] op_sel_hi:[1,0]
	v_cvt_f32_i32_e32 v23, v23
	v_pk_mul_f32 v[26:27], v[26:27], v[32:33]
	v_pk_mul_f32 v[32:33], v[124:125], v[140:141] op_sel_hi:[1,0]
	v_mul_f32_e32 v35, 0xbfb8aa3b, v26
	v_pk_mul_f32 v[30:31], v[32:33], v[30:31]
	v_cvt_f32_i32_e32 v33, v20
	v_cvt_f32_i32_e32 v32, v16
	v_cvt_f32_i32_e32 v20, v17
	v_pk_mul_f32 v[16:17], v[120:121], v[140:141] op_sel_hi:[1,0]
	v_mul_f32_e32 v36, 0xbfb8aa3b, v30
	v_pk_mul_f32 v[16:17], v[16:17], v[32:33]
	v_pk_mul_f32 v[32:33], v[118:119], v[140:141] op_sel_hi:[1,0]
	v_mul_f32_e32 v37, 0xbfb8aa3b, v16
	v_pk_mul_f32 v[20:21], v[32:33], v[20:21]
	v_cvt_f32_i32_e32 v33, v22
	v_cvt_f32_i32_e32 v32, v18
	v_cvt_f32_i32_e32 v22, v19
	v_pk_mul_f32 v[18:19], v[116:117], v[140:141] op_sel_hi:[1,0]
	v_mul_f32_e32 v38, 0xbfb8aa3b, v20
	v_pk_mul_f32 v[18:19], v[18:19], v[32:33]
	v_pk_mul_f32 v[32:33], v[114:115], v[140:141] op_sel_hi:[1,0]
	v_exp_f32_e32 v35, v35
	v_pk_mul_f32 v[22:23], v[32:33], v[22:23]
	v_mul_f32_e32 v32, 0xbfb8aa3b, v24
	v_mul_f32_e32 v33, 0xbfb8aa3b, v28
	v_exp_f32_e32 v32, v32
	v_exp_f32_e32 v33, v33
	v_exp_f32_e32 v36, v36
	v_exp_f32_e32 v37, v37
	v_exp_f32_e32 v38, v38
	v_mul_f32_e32 v39, 0xbfb8aa3b, v18
	v_mul_f32_e32 v40, 0xbfb8aa3b, v22
	v_mul_f32_e32 v16, v16, v17
	v_mul_f32_e32 v17, v20, v21
	v_add_f32_e32 v20, 1.0, v32
	v_add_f32_e32 v21, 1.0, v33
	v_exp_f32_e32 v39, v39
	v_exp_f32_e32 v40, v40
	v_mul_f32_e32 v24, v24, v25
	v_mul_f32_e32 v25, v28, v29
	v_mul_f32_e32 v18, v18, v19
	v_mul_f32_e32 v19, v22, v23
	v_rcp_f32_e32 v20, v20
	v_rcp_f32_e32 v21, v21
	v_add_f32_e32 v22, 1.0, v35
	v_add_f32_e32 v23, 1.0, v36
	v_add_f32_e32 v28, 1.0, v37
	v_add_f32_e32 v29, 1.0, v38
	v_rcp_f32_e32 v22, v22
	v_rcp_f32_e32 v23, v23
	v_rcp_f32_e32 v28, v28
	v_rcp_f32_e32 v29, v29
	v_mul_f32_e32 v26, v26, v27
	v_mul_f32_e32 v27, v30, v31
	v_add_f32_e32 v30, 1.0, v39
	v_add_f32_e32 v31, 1.0, v40
	v_mul_f32_e32 v20, v24, v20
	v_mul_f32_e32 v21, v25, v21
	v_rcp_f32_e32 v30, v30
	v_rcp_f32_e32 v31, v31
	v_mul_f32_e32 v22, v26, v22
	v_mul_f32_e32 v23, v27, v23
	v_mul_f32_e32 v24, v16, v28
	v_mul_f32_e32 v17, v17, v29
	v_med3_f32 v20, v20, s50, v152
	v_med3_f32 v21, v21, s50, v152
	v_mov_b32_e32 v16, 0
	v_cvt_pk_fp8_f32 v16, v20, v21
	v_med3_f32 v20, v22, s50, v152
	v_med3_f32 v21, v23, s50, v152
	v_med3_f32 v22, v24, s50, v152
	v_med3_f32 v23, v17, s50, v152
	v_mov_b32_e32 v17, 0
	v_cvt_pk_fp8_f32 v17, v22, v23
	v_mul_f32_e32 v18, v18, v30
	v_mul_f32_e32 v19, v19, v31
	v_med3_f32 v18, v18, s50, v152
	v_med3_f32 v19, v19, s50, v152
	v_cvt_pk_fp8_f32 v16, v20, v21 op_sel:[0,0,1]
	v_cvt_pk_fp8_f32 v17, v18, v19 op_sel:[0,0,1]
	v_add_u32_e32 v34, 0xa0, v134
	v_mad_i64_i32 v[18:19], s[22:23], v34, s51, v[122:123]
	v_lshl_add_u64 v[18:19], v[18:19], 0, v[132:133]
	global_store_dwordx2 v[18:19], v[16:17], off
	v_cvt_f32_i32_e32 v17, v12
	v_cvt_f32_i32_e32 v16, v8
	v_cvt_f32_i32_e32 v13, v13
	v_cvt_f32_i32_e32 v12, v9
	v_pk_mul_f32 v[8:9], v[138:139], v[112:113] op_sel_hi:[1,0]
	v_cvt_f32_i32_e32 v15, v15
	v_pk_mul_f32 v[8:9], v[8:9], v[16:17]
	v_pk_mul_f32 v[16:17], v[136:137], v[112:113] op_sel_hi:[1,0]
	v_cvt_f32_i32_e32 v5, v5
	v_pk_mul_f32 v[12:13], v[16:17], v[12:13]
	v_cvt_f32_i32_e32 v17, v14
	v_cvt_f32_i32_e32 v16, v10
	v_cvt_f32_i32_e32 v14, v11
	v_pk_mul_f32 v[10:11], v[126:127], v[112:113] op_sel_hi:[1,0]
	v_cvt_f32_i32_e32 v7, v7
	v_pk_mul_f32 v[10:11], v[10:11], v[16:17]
	v_pk_mul_f32 v[16:17], v[124:125], v[112:113] op_sel_hi:[1,0]
	v_mul_f32_e32 v19, 0xbfb8aa3b, v10
	v_pk_mul_f32 v[14:15], v[16:17], v[14:15]
	v_cvt_f32_i32_e32 v17, v4
	v_cvt_f32_i32_e32 v16, v0
	v_cvt_f32_i32_e32 v4, v1
	v_pk_mul_f32 v[0:1], v[120:121], v[112:113] op_sel_hi:[1,0]
	v_mul_f32_e32 v20, 0xbfb8aa3b, v14
	v_pk_mul_f32 v[0:1], v[0:1], v[16:17]
	v_pk_mul_f32 v[16:17], v[118:119], v[112:113] op_sel_hi:[1,0]
	v_mul_f32_e32 v21, 0xbfb8aa3b, v0
	v_pk_mul_f32 v[4:5], v[16:17], v[4:5]
	v_cvt_f32_i32_e32 v17, v6
	v_cvt_f32_i32_e32 v16, v2
	v_cvt_f32_i32_e32 v6, v3
	v_pk_mul_f32 v[2:3], v[116:117], v[112:113] op_sel_hi:[1,0]
	v_mul_f32_e32 v22, 0xbfb8aa3b, v4
	v_pk_mul_f32 v[2:3], v[2:3], v[16:17]
	v_pk_mul_f32 v[16:17], v[114:115], v[112:113] op_sel_hi:[1,0]
	v_exp_f32_e32 v19, v19
	v_pk_mul_f32 v[6:7], v[16:17], v[6:7]
	v_mul_f32_e32 v16, 0xbfb8aa3b, v8
	v_mul_f32_e32 v17, 0xbfb8aa3b, v12
	v_exp_f32_e32 v16, v16
	v_exp_f32_e32 v17, v17
	v_exp_f32_e32 v20, v20
	v_exp_f32_e32 v21, v21
	v_exp_f32_e32 v22, v22
	v_mul_f32_e32 v23, 0xbfb8aa3b, v2
	v_mul_f32_e32 v24, 0xbfb8aa3b, v6
	v_mul_f32_e32 v0, v0, v1
	v_mul_f32_e32 v1, v4, v5
	v_add_f32_e32 v4, 1.0, v16
	v_add_f32_e32 v5, 1.0, v17
	v_exp_f32_e32 v23, v23
	v_exp_f32_e32 v24, v24
	v_mul_f32_e32 v8, v8, v9
	v_mul_f32_e32 v9, v12, v13
	v_mul_f32_e32 v2, v2, v3
	v_mul_f32_e32 v3, v6, v7
	v_rcp_f32_e32 v4, v4
	v_rcp_f32_e32 v5, v5
	v_add_f32_e32 v6, 1.0, v19
	v_add_f32_e32 v7, 1.0, v20
	v_add_f32_e32 v12, 1.0, v21
	v_add_f32_e32 v13, 1.0, v22
	v_rcp_f32_e32 v6, v6
	v_rcp_f32_e32 v7, v7
	v_rcp_f32_e32 v12, v12
	v_rcp_f32_e32 v13, v13
	v_mul_f32_e32 v10, v10, v11
	v_mul_f32_e32 v11, v14, v15
	v_add_f32_e32 v14, 1.0, v23
	v_add_f32_e32 v15, 1.0, v24
	v_mul_f32_e32 v4, v8, v4
	v_mul_f32_e32 v5, v9, v5
	v_rcp_f32_e32 v14, v14
	v_rcp_f32_e32 v15, v15
	v_mul_f32_e32 v6, v10, v6
	v_mul_f32_e32 v7, v11, v7
	v_mul_f32_e32 v8, v0, v12
	v_mul_f32_e32 v1, v1, v13
	v_med3_f32 v4, v4, s50, v152
	v_med3_f32 v5, v5, s50, v152
	v_mov_b32_e32 v0, 0
	v_cvt_pk_fp8_f32 v0, v4, v5
	v_med3_f32 v4, v6, s50, v152
	v_med3_f32 v5, v7, s50, v152
	v_med3_f32 v6, v8, s50, v152
	v_med3_f32 v7, v1, s50, v152
	v_mov_b32_e32 v1, 0
	v_cvt_pk_fp8_f32 v1, v6, v7
	v_mul_f32_e32 v2, v2, v14
	v_mul_f32_e32 v3, v3, v15
	v_med3_f32 v2, v2, s50, v152
	v_med3_f32 v3, v3, s50, v152
	v_cvt_pk_fp8_f32 v0, v4, v5 op_sel:[0,0,1]
	v_cvt_pk_fp8_f32 v1, v2, v3 op_sel:[0,0,1]
	v_add_u32_e32 v18, 0xb0, v134
	v_mad_i64_i32 v[2:3], s[22:23], v18, s51, v[122:123]
	v_lshl_add_u64 v[2:3], v[2:3], 0, v[132:133]
	global_store_dwordx2 v[2:3], v[0:1], off
	s_andn2_b64 vcc, exec, s[0:1]
	s_mov_b64 s[0:1], -1
	s_cbranch_vccnz .LBB0_1556
	s_andn2_b64 vcc, exec, s[6:7]
	s_cbranch_vccnz .LBB0_1555
	s_barrier
	s_branch .LBB0_1555
